# v19 plus accumulator-chained MFMA order (k0,k1 of the same accumulator back to back; C forwarded), 44 K-loop blocks
# speedup vs baseline: 1.0224x; 1.0010x over previous
; #define PG8_STAGE(bufoff, gbase, voff) do { _Pragma("unroll") for (int _i = 0; _i < 2; ++_i) \
;         __builtin_amdgcn_global_load_lds((const unsigned*)((const char*)(gbase) + (voff)[_i]), (PG8_LAS unsigned*)(lds + (bufoff) + ldsw + _i * 8192), 16, 0, 0); } while (0)
; #define PG8_LDA(dst, b, h) do { _Pragma("unroll") for (int m = 0; m < 4; ++m) _Pragma("unroll") for (int k = 0; k < 2; ++k) dst[m][k] = *(const PG8_LAS bf16x8*)(lds + PG8_SA(b, h) + aoff + m * 2048 + k * 1024); } while (0)
; #define PG8_MMA(ai, bj, At, Bt) do { __builtin_amdgcn_s_setprio(1); _Pragma("unroll") for (int m = 0; m < 4; ++m) _Pragma("unroll") for (int n = 0; n < 2; ++n) _Pragma("unroll") for (int k = 0; k < 2; ++k) \
;         acc[ai][bj][m][n] = __builtin_amdgcn_mfma_f32_16x16x32_bf16(Bt[n][k], At[m][k], acc[ai][bj][m][n], 0, 0, 0); __builtin_amdgcn_s_setprio(0); } while (0)
; #define PG8_WAIT_V(n) asm volatile("s_waitcnt vmcnt(" #n ")" ::: "memory")
; #define PG8_WAIT_L(n) asm volatile("s_waitcnt lgkmcnt(" #n ")" ::: "memory")
; #define PG8_BAR __builtin_amdgcn_s_barrier()
; #define PG8_SCHED __builtin_amdgcn_sched_barrier(0)
; template <class Epi, class Sched, bool ALIGN_EPI = false, bool SP2 = false>
; __device__ __forceinline__ void gemm_phase(PG8_LAS unsigned char* lds, const Gemm g, const Sched& S, const Epi& E) {
;     ...
;             PG8_WAIT_V(8); PG8_WAIT_L(0); PG8_BAR; PG8_MMA(0, 0, At, B0); PG8_MMA(0, 1, At, B1); PG8_BAR; PG8_SCHED;
;             PG8_LDA(At, 0, 1); PG8_STAGE(PG8_SB(0, 0), b2, voffB); PG8_STAGE(PG8_SB(0, 1), b2 + hstep, voffB); PG8_STAGE(PG8_SA(0, 0), a2, voffA);
.Lrj_P1_0:
	s_waitcnt lgkmcnt(0)
	s_barrier
	s_setprio 1
	s_waitcnt lgkmcnt(0)
	v_mfma_f32_16x16x32_bf16 v[124:127], v[128:131], v[202:205], v[124:127]
	v_mfma_f32_16x16x32_bf16 v[124:127], v[132:135], v[206:209], v[124:127]
	v_mfma_f32_16x16x32_bf16 v[120:123], v[136:139], v[202:205], v[120:123]
	v_mfma_f32_16x16x32_bf16 v[120:123], v[140:143], v[206:209], v[120:123]
	v_mfma_f32_16x16x32_bf16 v[108:111], v[128:131], v[210:213], v[108:111]
	v_mfma_f32_16x16x32_bf16 v[108:111], v[132:135], v[214:217], v[108:111]
	v_mfma_f32_16x16x32_bf16 v[104:107], v[136:139], v[210:213], v[104:107]
	v_mfma_f32_16x16x32_bf16 v[104:107], v[140:143], v[214:217], v[104:107]
	v_mfma_f32_16x16x32_bf16 v[92:95], v[128:131], v[218:221], v[92:95]
	v_mfma_f32_16x16x32_bf16 v[92:95], v[132:135], v[222:225], v[92:95]
	v_mfma_f32_16x16x32_bf16 v[88:91], v[136:139], v[218:221], v[88:91]
	v_mfma_f32_16x16x32_bf16 v[88:91], v[140:143], v[222:225], v[88:91]
	v_mfma_f32_16x16x32_bf16 v[76:79], v[128:131], v[230:233], v[76:79]
	v_mfma_f32_16x16x32_bf16 v[76:79], v[132:135], v[234:237], v[76:79]
	v_mfma_f32_16x16x32_bf16 v[72:75], v[136:139], v[230:233], v[72:75]
	v_mfma_f32_16x16x32_bf16 v[72:75], v[140:143], v[234:237], v[72:75]
	s_setprio 0
	s_setprio 1
	v_mfma_f32_16x16x32_bf16 v[116:119], v[144:147], v[202:205], v[116:119]
	v_mfma_f32_16x16x32_bf16 v[116:119], v[148:151], v[206:209], v[116:119]
	v_mfma_f32_16x16x32_bf16 v[112:115], v[184:187], v[202:205], v[112:115]
	v_mfma_f32_16x16x32_bf16 v[112:115], v[188:191], v[206:209], v[112:115]
	v_mfma_f32_16x16x32_bf16 v[100:103], v[144:147], v[210:213], v[100:103]
	v_mfma_f32_16x16x32_bf16 v[100:103], v[148:151], v[214:217], v[100:103]
	v_mfma_f32_16x16x32_bf16 v[96:99], v[184:187], v[210:213], v[96:99]
	v_mfma_f32_16x16x32_bf16 v[96:99], v[188:191], v[214:217], v[96:99]
	v_mfma_f32_16x16x32_bf16 v[84:87], v[144:147], v[218:221], v[84:87]
	v_mfma_f32_16x16x32_bf16 v[84:87], v[148:151], v[222:225], v[84:87]
	v_mfma_f32_16x16x32_bf16 v[80:83], v[184:187], v[218:221], v[80:83]
	v_mfma_f32_16x16x32_bf16 v[80:83], v[188:191], v[222:225], v[80:83]
	v_mfma_f32_16x16x32_bf16 v[68:71], v[144:147], v[230:233], v[68:71]
	v_mfma_f32_16x16x32_bf16 v[68:71], v[148:151], v[234:237], v[68:71]
	v_mfma_f32_16x16x32_bf16 v[64:67], v[184:187], v[230:233], v[64:67]
	v_mfma_f32_16x16x32_bf16 v[64:67], v[188:191], v[234:237], v[64:67]
	s_setprio 0
	s_barrier
	s_add_i32 s29, s33, s74
	v_lshl_add_u64 v[192:193], s[6:7], 0, v[158:159]
	s_mov_b32 m0, s29
	ds_read_b128 v[202:205], v194 offset:16384
	ds_read_b128 v[206:209], v194 offset:17408
	ds_read_b128 v[210:213], v194 offset:18432
	ds_read_b128 v[214:217], v194 offset:19456
	ds_read_b128 v[218:221], v194 offset:20480
	ds_read_b128 v[222:225], v194 offset:21504
	ds_read_b128 v[230:233], v194 offset:22528
	ds_read_b128 v[234:237], v194 offset:23552
	global_load_lds_dwordx4 v[192:193], off
	s_add_i32 m0, s29, 0x2000
	s_add_u32 s38, s6, 0x40000
	v_lshl_add_u64 v[238:239], s[6:7], 0, v[162:163]
	s_addc_u32 s39, s7, 0
	s_add_i32 s29, s83, s74
	global_load_lds_dwordx4 v[238:239], off
	v_lshl_add_u64 v[240:241], s[38:39], 0, v[158:159]
	s_mov_b32 m0, s29
	v_lshl_add_u64 v[242:243], s[8:9], 0, v[160:161]
	global_load_lds_dwordx4 v[240:241], off
	v_lshl_add_u64 v[240:241], s[38:39], 0, v[162:163]
	s_add_i32 m0, s29, 0x2000
	s_nop 0
	global_load_lds_dwordx4 v[240:241], off
	v_lshl_add_u64 v[240:241], s[8:9], 0, v[156:157]
	s_mov_b32 m0, s37
	s_nop 0
	global_load_lds_dwordx4 v[240:241], off
	s_mov_b32 m0, s75
	s_nop 0
	global_load_lds_dwordx4 v[242:243], off
	s_cmp_eq_u32 s99, 1
	s_cbranch_scc1 .Lrw_P1_1
	s_waitcnt vmcnt(8)
	s_branch .Lrj_P1_1

; #define PG8_STAGE(bufoff, gbase, voff) do { _Pragma("unroll") for (int _i = 0; _i < 2; ++_i) \
;         __builtin_amdgcn_global_load_lds((const unsigned*)((const char*)(gbase) + (voff)[_i]), (PG8_LAS unsigned*)(lds + (bufoff) + ldsw + _i * 8192), 16, 0, 0); } while (0)
; #define PG8_LDA(dst, b, h) do { _Pragma("unroll") for (int m = 0; m < 4; ++m) _Pragma("unroll") for (int k = 0; k < 2; ++k) dst[m][k] = *(const PG8_LAS bf16x8*)(lds + PG8_SA(b, h) + aoff + m * 2048 + k * 1024); } while (0)
; #define PG8_LDB(dst, b, h) do { _Pragma("unroll") for (int n = 0; n < 2; ++n) _Pragma("unroll") for (int k = 0; k < 2; ++k) dst[n][k] = *(const PG8_LAS bf16x8*)(lds + PG8_SB(b, h) + boff + n * 2048 + k * 1024); } while (0)
; #define PG8_MMA(ai, bj, At, Bt) do { __builtin_amdgcn_s_setprio(1); _Pragma("unroll") for (int m = 0; m < 4; ++m) _Pragma("unroll") for (int n = 0; n < 2; ++n) _Pragma("unroll") for (int k = 0; k < 2; ++k) \
;         acc[ai][bj][m][n] = __builtin_amdgcn_mfma_f32_16x16x32_bf16(Bt[n][k], At[m][k], acc[ai][bj][m][n], 0, 0, 0); __builtin_amdgcn_s_setprio(0); } while (0)
; #define PG8_WAIT_V(n) asm volatile("s_waitcnt vmcnt(" #n ")" ::: "memory")
; #define PG8_WAIT_L(n) asm volatile("s_waitcnt lgkmcnt(" #n ")" ::: "memory")
; #define PG8_BAR __builtin_amdgcn_s_barrier()
; #define PG8_SCHED __builtin_amdgcn_sched_barrier(0)
; template <class Epi, class Sched, bool ALIGN_EPI = false, bool SP2 = false>
; __device__ __forceinline__ void gemm_phase(PG8_LAS unsigned char* lds, const Gemm g, const Sched& S, const Epi& E) {
;     ...
;             PG8_WAIT_V(8); PG8_WAIT_L(0); PG8_BAR; PG8_MMA(1, 0, At, B0); PG8_MMA(1, 1, At, B1); PG8_BAR; PG8_SCHED;
;             PG8_LDB(B0, 1, 0); PG8_LDB(B1, 1, 1); PG8_SCHED; PG8_LDA(At, 1, 0); PG8_STAGE(PG8_SA(0, 1), a2 + hstep, voffA);
;             PG8_WAIT_V(8); PG8_WAIT_L(0); PG8_BAR; PG8_MMA(0, 0, At, B0); PG8_MMA(0, 1, At, B1); PG8_BAR; PG8_SCHED;
.Lrj_P1_1:
	s_waitcnt lgkmcnt(0)
	s_barrier
	s_setprio 1
	s_waitcnt lgkmcnt(0)
	v_mfma_f32_16x16x32_bf16 v[60:63], v[128:131], v[202:205], v[60:63]
	v_mfma_f32_16x16x32_bf16 v[60:63], v[132:135], v[206:209], v[60:63]
	v_mfma_f32_16x16x32_bf16 v[56:59], v[136:139], v[202:205], v[56:59]
	v_mfma_f32_16x16x32_bf16 v[56:59], v[140:143], v[206:209], v[56:59]
	v_mfma_f32_16x16x32_bf16 v[44:47], v[128:131], v[210:213], v[44:47]
	v_mfma_f32_16x16x32_bf16 v[44:47], v[132:135], v[214:217], v[44:47]
	v_mfma_f32_16x16x32_bf16 v[40:43], v[136:139], v[210:213], v[40:43]
	v_mfma_f32_16x16x32_bf16 v[40:43], v[140:143], v[214:217], v[40:43]
	v_mfma_f32_16x16x32_bf16 v[28:31], v[128:131], v[218:221], v[28:31]
	v_mfma_f32_16x16x32_bf16 v[28:31], v[132:135], v[222:225], v[28:31]
	v_mfma_f32_16x16x32_bf16 v[24:27], v[136:139], v[218:221], v[24:27]
	v_mfma_f32_16x16x32_bf16 v[24:27], v[140:143], v[222:225], v[24:27]
	v_mfma_f32_16x16x32_bf16 v[12:15], v[128:131], v[230:233], v[12:15]
	v_mfma_f32_16x16x32_bf16 v[12:15], v[132:135], v[234:237], v[12:15]
	v_mfma_f32_16x16x32_bf16 v[8:11], v[136:139], v[230:233], v[8:11]
	v_mfma_f32_16x16x32_bf16 v[8:11], v[140:143], v[234:237], v[8:11]
	s_setprio 0
	s_setprio 1
	v_mfma_f32_16x16x32_bf16 v[52:55], v[144:147], v[202:205], v[52:55]
	v_mfma_f32_16x16x32_bf16 v[52:55], v[148:151], v[206:209], v[52:55]
	v_mfma_f32_16x16x32_bf16 v[48:51], v[184:187], v[202:205], v[48:51]
	v_mfma_f32_16x16x32_bf16 v[48:51], v[188:191], v[206:209], v[48:51]
	v_mfma_f32_16x16x32_bf16 v[36:39], v[144:147], v[210:213], v[36:39]
	v_mfma_f32_16x16x32_bf16 v[36:39], v[148:151], v[214:217], v[36:39]
	v_mfma_f32_16x16x32_bf16 v[32:35], v[184:187], v[210:213], v[32:35]
	v_mfma_f32_16x16x32_bf16 v[32:35], v[188:191], v[214:217], v[32:35]
	v_mfma_f32_16x16x32_bf16 v[20:23], v[144:147], v[218:221], v[20:23]
	v_mfma_f32_16x16x32_bf16 v[20:23], v[148:151], v[222:225], v[20:23]
	v_mfma_f32_16x16x32_bf16 v[16:19], v[184:187], v[218:221], v[16:19]
	v_mfma_f32_16x16x32_bf16 v[16:19], v[188:191], v[222:225], v[16:19]
	v_mfma_f32_16x16x32_bf16 v[4:7], v[144:147], v[230:233], v[4:7]
	v_mfma_f32_16x16x32_bf16 v[4:7], v[148:151], v[234:237], v[4:7]
	v_mfma_f32_16x16x32_bf16 v[0:3], v[184:187], v[230:233], v[0:3]
	v_mfma_f32_16x16x32_bf16 v[0:3], v[188:191], v[234:237], v[0:3]
	s_setprio 0
	s_barrier
	s_add_i32 s29, 0, 0x18000
	s_add_i32 s38, 0, 0x1c000
	v_add_u32_e32 v140, s29, v169
	v_add_u32_e32 v164, s38, v169
	ds_read_b128 v[128:131], v140
	ds_read_b128 v[132:135], v140 offset:1024
	ds_read_b128 v[136:139], v140 offset:2048
	ds_read_b128 v[140:143], v140 offset:3072
	ds_read_b128 v[144:147], v164
	ds_read_b128 v[148:151], v164 offset:1024
	ds_read_b128 v[184:187], v164 offset:2048
	ds_read_b128 v[188:191], v164 offset:3072
	s_add_u32 s8, s8, 0x40000
	s_addc_u32 s9, s9, 0
	s_mov_b32 m0, s76
	v_lshl_add_u64 v[244:245], s[8:9], 0, v[156:157]
	ds_read_b128 v[202:205], v194 offset:32768
	ds_read_b128 v[206:209], v194 offset:33792
	ds_read_b128 v[210:213], v194 offset:34816
	ds_read_b128 v[214:217], v194 offset:35840
	ds_read_b128 v[218:221], v194 offset:36864
	ds_read_b128 v[222:225], v194 offset:37888
	ds_read_b128 v[230:233], v194 offset:38912
	ds_read_b128 v[234:237], v194 offset:39936
	global_load_lds_dwordx4 v[244:245], off
	v_lshl_add_u64 v[244:245], s[8:9], 0, v[160:161]
	s_mov_b32 m0, s77
	s_nop 0
	global_load_lds_dwordx4 v[244:245], off
	s_waitcnt vmcnt(8)
	s_waitcnt lgkmcnt(0)
	s_barrier
	s_setprio 1
	s_waitcnt lgkmcnt(0)
	v_mfma_f32_16x16x32_bf16 v[124:127], v[128:131], v[202:205], v[124:127]
	v_mfma_f32_16x16x32_bf16 v[124:127], v[132:135], v[206:209], v[124:127]
	v_mfma_f32_16x16x32_bf16 v[120:123], v[136:139], v[202:205], v[120:123]
	v_mfma_f32_16x16x32_bf16 v[120:123], v[140:143], v[206:209], v[120:123]
	v_mfma_f32_16x16x32_bf16 v[108:111], v[128:131], v[210:213], v[108:111]
	v_mfma_f32_16x16x32_bf16 v[108:111], v[132:135], v[214:217], v[108:111]
	v_mfma_f32_16x16x32_bf16 v[104:107], v[136:139], v[210:213], v[104:107]
	v_mfma_f32_16x16x32_bf16 v[104:107], v[140:143], v[214:217], v[104:107]
	v_mfma_f32_16x16x32_bf16 v[92:95], v[128:131], v[218:221], v[92:95]
	v_mfma_f32_16x16x32_bf16 v[92:95], v[132:135], v[222:225], v[92:95]
	v_mfma_f32_16x16x32_bf16 v[88:91], v[136:139], v[218:221], v[88:91]
	v_mfma_f32_16x16x32_bf16 v[88:91], v[140:143], v[222:225], v[88:91]
	v_mfma_f32_16x16x32_bf16 v[76:79], v[128:131], v[230:233], v[76:79]
	v_mfma_f32_16x16x32_bf16 v[76:79], v[132:135], v[234:237], v[76:79]
	v_mfma_f32_16x16x32_bf16 v[72:75], v[136:139], v[230:233], v[72:75]
	v_mfma_f32_16x16x32_bf16 v[72:75], v[140:143], v[234:237], v[72:75]
	s_setprio 0
	s_setprio 1
	v_mfma_f32_16x16x32_bf16 v[116:119], v[144:147], v[202:205], v[116:119]
	v_mfma_f32_16x16x32_bf16 v[116:119], v[148:151], v[206:209], v[116:119]
	v_mfma_f32_16x16x32_bf16 v[112:115], v[184:187], v[202:205], v[112:115]
	v_mfma_f32_16x16x32_bf16 v[112:115], v[188:191], v[206:209], v[112:115]
	v_mfma_f32_16x16x32_bf16 v[100:103], v[144:147], v[210:213], v[100:103]
	v_mfma_f32_16x16x32_bf16 v[100:103], v[148:151], v[214:217], v[100:103]
	v_mfma_f32_16x16x32_bf16 v[96:99], v[184:187], v[210:213], v[96:99]
	v_mfma_f32_16x16x32_bf16 v[96:99], v[188:191], v[214:217], v[96:99]
	v_mfma_f32_16x16x32_bf16 v[84:87], v[144:147], v[218:221], v[84:87]
	v_mfma_f32_16x16x32_bf16 v[84:87], v[148:151], v[222:225], v[84:87]
	v_mfma_f32_16x16x32_bf16 v[80:83], v[184:187], v[218:221], v[80:83]
	v_mfma_f32_16x16x32_bf16 v[80:83], v[188:191], v[222:225], v[80:83]
	v_mfma_f32_16x16x32_bf16 v[68:71], v[144:147], v[230:233], v[68:71]
	v_mfma_f32_16x16x32_bf16 v[68:71], v[148:151], v[234:237], v[68:71]
	v_mfma_f32_16x16x32_bf16 v[64:67], v[184:187], v[230:233], v[64:67]
	v_mfma_f32_16x16x32_bf16 v[64:67], v[188:191], v[234:237], v[64:67]
	s_setprio 0
	s_barrier
; #define PG8_STAGE(bufoff, gbase, voff) do { _Pragma("unroll") for (int _i = 0; _i < 2; ++_i) \
;         __builtin_amdgcn_global_load_lds((const unsigned*)((const char*)(gbase) + (voff)[_i]), (PG8_LAS unsigned*)(lds + (bufoff) + ldsw + _i * 8192), 16, 0, 0); } while (0)
; #define PG8_LDA(dst, b, h) do { _Pragma("unroll") for (int m = 0; m < 4; ++m) _Pragma("unroll") for (int k = 0; k < 2; ++k) dst[m][k] = *(const PG8_LAS bf16x8*)(lds + PG8_SA(b, h) + aoff + m * 2048 + k * 1024); } while (0)
; #define PG8_MMA(ai, bj, At, Bt) do { __builtin_amdgcn_s_setprio(1); _Pragma("unroll") for (int m = 0; m < 4; ++m) _Pragma("unroll") for (int n = 0; n < 2; ++n) _Pragma("unroll") for (int k = 0; k < 2; ++k) \
;         acc[ai][bj][m][n] = __builtin_amdgcn_mfma_f32_16x16x32_bf16(Bt[n][k], At[m][k], acc[ai][bj][m][n], 0, 0, 0); __builtin_amdgcn_s_setprio(0); } while (0)
; #define PG8_WAIT_V(n) asm volatile("s_waitcnt vmcnt(" #n ")" ::: "memory")
; #define PG8_WAIT_L(n) asm volatile("s_waitcnt lgkmcnt(" #n ")" ::: "memory")
; #define PG8_BAR __builtin_amdgcn_s_barrier()
; #define PG8_SCHED __builtin_amdgcn_sched_barrier(0)
; template <class Epi, class Sched, bool ALIGN_EPI = false, bool SP2 = false>
; __device__ __forceinline__ void gemm_phase(PG8_LAS unsigned char* lds, const Gemm g, const Sched& S, const Epi& E) {
;     ...
;             PG8_LDA(At, 1, 1); PG8_STAGE(PG8_SB(1, 0), b3, voffB); PG8_STAGE(PG8_SB(1, 1), b3 + hstep, voffB); PG8_STAGE(PG8_SA(1, 0), a3, voffA);
;             PG8_WAIT_V(8); PG8_WAIT_L(0); PG8_BAR; PG8_MMA(1, 0, At, B0); PG8_MMA(1, 1, At, B1); PG8_BAR; PG8_SCHED;
;     ...
;         if constexpr (ALIGN_EPI) { if (wr == 0) PG8_BAR; }
	s_add_i32 s8, s29, s74
	v_lshl_add_u64 v[192:193], v[192:193], 0, s[22:23]
	s_mov_b32 m0, s8
	ds_read_b128 v[202:205], v194 offset:49152
	ds_read_b128 v[206:209], v194 offset:50176
	ds_read_b128 v[210:213], v194 offset:51200
	ds_read_b128 v[214:217], v194 offset:52224
	ds_read_b128 v[218:221], v194 offset:53248
	ds_read_b128 v[222:225], v194 offset:54272
	ds_read_b128 v[230:233], v194 offset:55296
	ds_read_b128 v[234:237], v194 offset:56320
	global_load_lds_dwordx4 v[192:193], off
	s_add_i32 m0, s8, 0x2000
	s_add_u32 s6, s6, 0x40080
	v_lshl_add_u64 v[192:193], v[238:239], 0, s[22:23]
	s_addc_u32 s7, s7, 0
	s_add_i32 s8, s38, s74
	global_load_lds_dwordx4 v[192:193], off
	v_lshl_add_u64 v[192:193], s[6:7], 0, v[158:159]
	s_mov_b32 m0, s8
	s_nop 0
	global_load_lds_dwordx4 v[192:193], off
	v_lshl_add_u64 v[192:193], s[6:7], 0, v[162:163]
	s_add_i32 m0, s8, 0x2000
	s_nop 0
	global_load_lds_dwordx4 v[192:193], off
	v_lshl_add_u64 v[192:193], v[240:241], 0, s[22:23]
	s_mov_b32 m0, s95
	s_nop 0
	global_load_lds_dwordx4 v[192:193], off
	v_lshl_add_u64 v[192:193], v[242:243], 0, s[22:23]
	s_mov_b32 m0, s96
	s_nop 0
	global_load_lds_dwordx4 v[192:193], off
	s_waitcnt vmcnt(8)
	s_waitcnt lgkmcnt(0)
	s_barrier
	s_setprio 1
	s_waitcnt lgkmcnt(0)
	v_mfma_f32_16x16x32_bf16 v[60:63], v[128:131], v[202:205], v[60:63]
	v_mfma_f32_16x16x32_bf16 v[60:63], v[132:135], v[206:209], v[60:63]
	v_mfma_f32_16x16x32_bf16 v[56:59], v[136:139], v[202:205], v[56:59]
	v_mfma_f32_16x16x32_bf16 v[56:59], v[140:143], v[206:209], v[56:59]
	v_mfma_f32_16x16x32_bf16 v[44:47], v[128:131], v[210:213], v[44:47]
	v_mfma_f32_16x16x32_bf16 v[44:47], v[132:135], v[214:217], v[44:47]
	v_mfma_f32_16x16x32_bf16 v[40:43], v[136:139], v[210:213], v[40:43]
	v_mfma_f32_16x16x32_bf16 v[40:43], v[140:143], v[214:217], v[40:43]
	v_mfma_f32_16x16x32_bf16 v[28:31], v[128:131], v[218:221], v[28:31]
	v_mfma_f32_16x16x32_bf16 v[28:31], v[132:135], v[222:225], v[28:31]
	v_mfma_f32_16x16x32_bf16 v[24:27], v[136:139], v[218:221], v[24:27]
	v_mfma_f32_16x16x32_bf16 v[24:27], v[140:143], v[222:225], v[24:27]
	v_mfma_f32_16x16x32_bf16 v[12:15], v[128:131], v[230:233], v[12:15]
	v_mfma_f32_16x16x32_bf16 v[12:15], v[132:135], v[234:237], v[12:15]
	v_mfma_f32_16x16x32_bf16 v[8:11], v[136:139], v[230:233], v[8:11]
	v_mfma_f32_16x16x32_bf16 v[8:11], v[140:143], v[234:237], v[8:11]
	s_setprio 0
	s_setprio 1
	v_mfma_f32_16x16x32_bf16 v[52:55], v[144:147], v[202:205], v[52:55]
	v_mfma_f32_16x16x32_bf16 v[52:55], v[148:151], v[206:209], v[52:55]
	v_mfma_f32_16x16x32_bf16 v[48:51], v[184:187], v[202:205], v[48:51]
	v_mfma_f32_16x16x32_bf16 v[48:51], v[188:191], v[206:209], v[48:51]
	v_mfma_f32_16x16x32_bf16 v[36:39], v[144:147], v[210:213], v[36:39]
	v_mfma_f32_16x16x32_bf16 v[36:39], v[148:151], v[214:217], v[36:39]
	v_mfma_f32_16x16x32_bf16 v[32:35], v[184:187], v[210:213], v[32:35]
	v_mfma_f32_16x16x32_bf16 v[32:35], v[188:191], v[214:217], v[32:35]
	v_mfma_f32_16x16x32_bf16 v[20:23], v[144:147], v[218:221], v[20:23]
	v_mfma_f32_16x16x32_bf16 v[20:23], v[148:151], v[222:225], v[20:23]
	v_mfma_f32_16x16x32_bf16 v[16:19], v[184:187], v[218:221], v[16:19]
	v_mfma_f32_16x16x32_bf16 v[16:19], v[188:191], v[222:225], v[16:19]
	v_mfma_f32_16x16x32_bf16 v[4:7], v[144:147], v[230:233], v[4:7]
	v_mfma_f32_16x16x32_bf16 v[4:7], v[148:151], v[234:237], v[4:7]
	v_mfma_f32_16x16x32_bf16 v[0:3], v[184:187], v[230:233], v[0:3]
	v_mfma_f32_16x16x32_bf16 v[0:3], v[188:191], v[234:237], v[0:3]
	s_setprio 0
	s_barrier
	s_mov_b32 s99, 0
	s_add_i32 s27, s27, 2
	s_add_u32 s4, s4, 0x100
	s_addc_u32 s5, s5, 0
	s_add_u32 s24, s24, 0x100
	s_addc_u32 s25, s25, 0
	s_cmp_gt_u32 s27, 13
	s_cbranch_scc0 .LBB0_121
	s_and_b64 vcc, exec, s[70:71]
	s_cbranch_vccz .LBB0_124
	s_barrier

; #define PG8_STAGE(bufoff, gbase, voff) do { _Pragma("unroll") for (int _i = 0; _i < 2; ++_i) \
;         __builtin_amdgcn_global_load_lds((const unsigned*)((const char*)(gbase) + (voff)[_i]), (PG8_LAS unsigned*)(lds + (bufoff) + ldsw + _i * 8192), 16, 0, 0); } while (0)
; #define PG8_LDA(dst, b, h) do { _Pragma("unroll") for (int m = 0; m < 4; ++m) _Pragma("unroll") for (int k = 0; k < 2; ++k) dst[m][k] = *(const PG8_LAS bf16x8*)(lds + PG8_SA(b, h) + aoff + m * 2048 + k * 1024); } while (0)
; #define PG8_MMA(ai, bj, At, Bt) do { __builtin_amdgcn_s_setprio(1); _Pragma("unroll") for (int m = 0; m < 4; ++m) _Pragma("unroll") for (int n = 0; n < 2; ++n) _Pragma("unroll") for (int k = 0; k < 2; ++k) \
;         acc[ai][bj][m][n] = __builtin_amdgcn_mfma_f32_16x16x32_bf16(Bt[n][k], At[m][k], acc[ai][bj][m][n], 0, 0, 0); __builtin_amdgcn_s_setprio(0); } while (0)
; #define PG8_WAIT_V(n) asm volatile("s_waitcnt vmcnt(" #n ")" ::: "memory")
; #define PG8_WAIT_L(n) asm volatile("s_waitcnt lgkmcnt(" #n ")" ::: "memory")
; #define PG8_BAR __builtin_amdgcn_s_barrier()
; #define PG8_SCHED __builtin_amdgcn_sched_barrier(0)
; template <class Epi, class Sched, bool ALIGN_EPI = false, bool SP2 = false>
; __device__ __forceinline__ void gemm_phase(PG8_LAS unsigned char* lds, const Gemm g, const Sched& S, const Epi& E) {
;     ...
;             PG8_WAIT_V(8); PG8_WAIT_L(0); PG8_BAR; PG8_MMA(0, 0, At, B0); PG8_MMA(0, 1, At, B1); PG8_BAR; PG8_SCHED;
;             PG8_LDA(At, 0, 1); PG8_STAGE(PG8_SB(0, 0), b2, voffB); PG8_STAGE(PG8_SB(0, 1), b2 + hstep, voffB); PG8_STAGE(PG8_SA(0, 0), a2, voffA);
.Lrj_P3a_0:
	s_waitcnt lgkmcnt(0)
	s_barrier
	s_setprio 1
	s_waitcnt lgkmcnt(0)
	v_mfma_f32_16x16x32_bf16 v[124:127], v[144:147], v[184:187], v[124:127]
	v_mfma_f32_16x16x32_bf16 v[124:127], v[156:159], v[188:191], v[124:127]
	v_mfma_f32_16x16x32_bf16 v[120:123], v[160:163], v[184:187], v[120:123]
	v_mfma_f32_16x16x32_bf16 v[120:123], v[164:167], v[188:191], v[120:123]
	v_mfma_f32_16x16x32_bf16 v[112:115], v[144:147], v[192:195], v[112:115]
	v_mfma_f32_16x16x32_bf16 v[112:115], v[156:159], v[196:199], v[112:115]
	v_mfma_f32_16x16x32_bf16 v[104:107], v[160:163], v[192:195], v[104:107]
	v_mfma_f32_16x16x32_bf16 v[104:107], v[164:167], v[196:199], v[104:107]
	v_mfma_f32_16x16x32_bf16 v[96:99], v[144:147], v[200:203], v[96:99]
	v_mfma_f32_16x16x32_bf16 v[96:99], v[156:159], v[204:207], v[96:99]
	v_mfma_f32_16x16x32_bf16 v[88:91], v[160:163], v[200:203], v[88:91]
	v_mfma_f32_16x16x32_bf16 v[88:91], v[164:167], v[204:207], v[88:91]
	v_mfma_f32_16x16x32_bf16 v[80:83], v[144:147], v[208:211], v[80:83]
	v_mfma_f32_16x16x32_bf16 v[80:83], v[156:159], v[212:215], v[80:83]
	v_mfma_f32_16x16x32_bf16 v[72:75], v[160:163], v[208:211], v[72:75]
	v_mfma_f32_16x16x32_bf16 v[72:75], v[164:167], v[212:215], v[72:75]
	s_setprio 0
	s_setprio 1
	v_mfma_f32_16x16x32_bf16 v[116:119], v[168:171], v[184:187], v[116:119]
	v_mfma_f32_16x16x32_bf16 v[116:119], v[172:175], v[188:191], v[116:119]
	v_mfma_f32_16x16x32_bf16 v[108:111], v[176:179], v[184:187], v[108:111]
	v_mfma_f32_16x16x32_bf16 v[108:111], v[180:183], v[188:191], v[108:111]
	v_mfma_f32_16x16x32_bf16 v[100:103], v[168:171], v[192:195], v[100:103]
	v_mfma_f32_16x16x32_bf16 v[100:103], v[172:175], v[196:199], v[100:103]
	v_mfma_f32_16x16x32_bf16 v[92:95], v[176:179], v[192:195], v[92:95]
	v_mfma_f32_16x16x32_bf16 v[92:95], v[180:183], v[196:199], v[92:95]
	v_mfma_f32_16x16x32_bf16 v[84:87], v[168:171], v[200:203], v[84:87]
	v_mfma_f32_16x16x32_bf16 v[84:87], v[172:175], v[204:207], v[84:87]
	v_mfma_f32_16x16x32_bf16 v[76:79], v[176:179], v[200:203], v[76:79]
	v_mfma_f32_16x16x32_bf16 v[76:79], v[180:183], v[204:207], v[76:79]
	v_mfma_f32_16x16x32_bf16 v[68:71], v[168:171], v[208:211], v[68:71]
	v_mfma_f32_16x16x32_bf16 v[68:71], v[172:175], v[212:215], v[68:71]
	v_mfma_f32_16x16x32_bf16 v[64:67], v[176:179], v[208:211], v[64:67]
	v_mfma_f32_16x16x32_bf16 v[64:67], v[180:183], v[212:215], v[64:67]
	s_setprio 0
	s_barrier
	s_add_i32 s75, s67, s43
	v_lshl_add_u64 v[148:149], s[38:39], 0, v[132:133]
	s_mov_b32 m0, s75
	ds_read_b128 v[184:187], v155 offset:16384
	ds_read_b128 v[188:191], v155 offset:17408
	ds_read_b128 v[192:195], v155 offset:18432
	ds_read_b128 v[196:199], v155 offset:19456
	ds_read_b128 v[200:203], v155 offset:20480
	ds_read_b128 v[204:207], v155 offset:21504
	ds_read_b128 v[208:211], v155 offset:22528
	ds_read_b128 v[212:215], v155 offset:23552
	global_load_lds_dwordx4 v[148:149], off
	s_add_i32 m0, s75, 0x2000
	s_add_u32 s76, s38, 0x20000
	v_lshl_add_u64 v[216:217], s[38:39], 0, v[128:129]
	s_addc_u32 s77, s39, 0
	s_add_i32 s75, s68, s43
	global_load_lds_dwordx4 v[216:217], off
	v_lshl_add_u64 v[218:219], s[76:77], 0, v[132:133]
	s_mov_b32 m0, s75
	v_lshl_add_u64 v[220:221], s[40:41], 0, v[130:131]
	global_load_lds_dwordx4 v[218:219], off
	v_lshl_add_u64 v[218:219], s[76:77], 0, v[128:129]
	s_add_i32 m0, s75, 0x2000
	s_nop 0
	global_load_lds_dwordx4 v[218:219], off
	v_lshl_add_u64 v[218:219], s[40:41], 0, v[134:135]
	s_mov_b32 m0, s35
	s_nop 0
	global_load_lds_dwordx4 v[218:219], off
	s_mov_b32 m0, s52
	s_nop 0
	global_load_lds_dwordx4 v[220:221], off
	s_cmp_eq_u32 s99, 1
	s_cbranch_scc1 .Lrw_P3a_1
	s_waitcnt vmcnt(8)
	s_branch .Lrj_P3a_1

; #define PG8_STAGE(bufoff, gbase, voff) do { _Pragma("unroll") for (int _i = 0; _i < 2; ++_i) \
;         __builtin_amdgcn_global_load_lds((const unsigned*)((const char*)(gbase) + (voff)[_i]), (PG8_LAS unsigned*)(lds + (bufoff) + ldsw + _i * 8192), 16, 0, 0); } while (0)
; #define PG8_LDA(dst, b, h) do { _Pragma("unroll") for (int m = 0; m < 4; ++m) _Pragma("unroll") for (int k = 0; k < 2; ++k) dst[m][k] = *(const PG8_LAS bf16x8*)(lds + PG8_SA(b, h) + aoff + m * 2048 + k * 1024); } while (0)
; #define PG8_LDB(dst, b, h) do { _Pragma("unroll") for (int n = 0; n < 2; ++n) _Pragma("unroll") for (int k = 0; k < 2; ++k) dst[n][k] = *(const PG8_LAS bf16x8*)(lds + PG8_SB(b, h) + boff + n * 2048 + k * 1024); } while (0)
; #define PG8_MMA(ai, bj, At, Bt) do { __builtin_amdgcn_s_setprio(1); _Pragma("unroll") for (int m = 0; m < 4; ++m) _Pragma("unroll") for (int n = 0; n < 2; ++n) _Pragma("unroll") for (int k = 0; k < 2; ++k) \
;         acc[ai][bj][m][n] = __builtin_amdgcn_mfma_f32_16x16x32_bf16(Bt[n][k], At[m][k], acc[ai][bj][m][n], 0, 0, 0); __builtin_amdgcn_s_setprio(0); } while (0)
; #define PG8_WAIT_V(n) asm volatile("s_waitcnt vmcnt(" #n ")" ::: "memory")
; template <class Epi, class Sched, bool ALIGN_EPI = false, bool SP2 = false>
; __device__ __forceinline__ void gemm_phase(PG8_LAS unsigned char* lds, const Gemm g, const Sched& S, const Epi& E) {
;     ...
;             PG8_LDB(B0, 0, 0); PG8_LDB(B1, 0, 1); PG8_SCHED; PG8_LDA(At, 0, 0); PG8_STAGE(PG8_SA(1, 1), a1 + hstep, voffA);
;             PG8_WAIT_V(8); PG8_WAIT_L(0); PG8_BAR; PG8_MMA(0, 0, At, B0); PG8_MMA(0, 1, At, B1); PG8_BAR; PG8_SCHED;
;             PG8_LDA(At, 0, 1); PG8_STAGE(PG8_SB(0, 0), b2, voffB); PG8_STAGE(PG8_SB(0, 1), b2 + hstep, voffB); PG8_STAGE(PG8_SA(0, 0), a2, voffA);
;             PG8_WAIT_V(8); PG8_WAIT_L(0); PG8_BAR; PG8_MMA(1, 0, At, B0); PG8_MMA(1, 1, At, B1); PG8_BAR; PG8_SCHED;
;             PG8_LDB(B0, 1, 0); PG8_LDB(B1, 1, 1); PG8_SCHED; PG8_LDA(At, 1, 0); PG8_STAGE(PG8_SA(0, 1), a2 + hstep, voffA);
;             PG8_WAIT_V(8); PG8_WAIT_L(0); PG8_BAR; PG8_MMA(0, 0, At, B0); PG8_MMA(0, 1, At, B1); PG8_BAR; PG8_SCHED;
;             PG8_LDA(At, 1, 1); PG8_STAGE(PG8_SB(1, 0), b3, voffB); PG8_STAGE(PG8_SB(1, 1), b3 + hstep, voffB); PG8_STAGE(PG8_SA(1, 0), a3, voffA);
;             PG8_WAIT_V(8); PG8_WAIT_L(0); PG8_BAR; PG8_MMA(1, 0, At, B0); PG8_MMA(1, 1, At, B1); PG8_BAR; PG8_SCHED;
.Lrj_P3a_1:
	s_waitcnt lgkmcnt(0)
	s_barrier
	s_setprio 1
	s_waitcnt lgkmcnt(0)
	v_mfma_f32_16x16x32_bf16 v[60:63], v[144:147], v[184:187], v[60:63]
	v_mfma_f32_16x16x32_bf16 v[60:63], v[156:159], v[188:191], v[60:63]
	v_mfma_f32_16x16x32_bf16 v[56:59], v[160:163], v[184:187], v[56:59]
	v_mfma_f32_16x16x32_bf16 v[56:59], v[164:167], v[188:191], v[56:59]
	v_mfma_f32_16x16x32_bf16 v[48:51], v[144:147], v[192:195], v[48:51]
	v_mfma_f32_16x16x32_bf16 v[48:51], v[156:159], v[196:199], v[48:51]
	v_mfma_f32_16x16x32_bf16 v[40:43], v[160:163], v[192:195], v[40:43]
	v_mfma_f32_16x16x32_bf16 v[40:43], v[164:167], v[196:199], v[40:43]
	v_mfma_f32_16x16x32_bf16 v[32:35], v[144:147], v[200:203], v[32:35]
	v_mfma_f32_16x16x32_bf16 v[32:35], v[156:159], v[204:207], v[32:35]
	v_mfma_f32_16x16x32_bf16 v[24:27], v[160:163], v[200:203], v[24:27]
	v_mfma_f32_16x16x32_bf16 v[24:27], v[164:167], v[204:207], v[24:27]
	v_mfma_f32_16x16x32_bf16 v[16:19], v[144:147], v[208:211], v[16:19]
	v_mfma_f32_16x16x32_bf16 v[16:19], v[156:159], v[212:215], v[16:19]
	v_mfma_f32_16x16x32_bf16 v[8:11], v[160:163], v[208:211], v[8:11]
	v_mfma_f32_16x16x32_bf16 v[8:11], v[164:167], v[212:215], v[8:11]
	s_setprio 0
	s_setprio 1
	v_mfma_f32_16x16x32_bf16 v[52:55], v[168:171], v[184:187], v[52:55]
	v_mfma_f32_16x16x32_bf16 v[52:55], v[172:175], v[188:191], v[52:55]
	v_mfma_f32_16x16x32_bf16 v[44:47], v[176:179], v[184:187], v[44:47]
	v_mfma_f32_16x16x32_bf16 v[44:47], v[180:183], v[188:191], v[44:47]
	v_mfma_f32_16x16x32_bf16 v[36:39], v[168:171], v[192:195], v[36:39]
	v_mfma_f32_16x16x32_bf16 v[36:39], v[172:175], v[196:199], v[36:39]
	v_mfma_f32_16x16x32_bf16 v[28:31], v[176:179], v[192:195], v[28:31]
	v_mfma_f32_16x16x32_bf16 v[28:31], v[180:183], v[196:199], v[28:31]
	v_mfma_f32_16x16x32_bf16 v[20:23], v[168:171], v[200:203], v[20:23]
	v_mfma_f32_16x16x32_bf16 v[20:23], v[172:175], v[204:207], v[20:23]
	v_mfma_f32_16x16x32_bf16 v[12:15], v[176:179], v[200:203], v[12:15]
	v_mfma_f32_16x16x32_bf16 v[12:15], v[180:183], v[204:207], v[12:15]
	v_mfma_f32_16x16x32_bf16 v[4:7], v[168:171], v[208:211], v[4:7]
	v_mfma_f32_16x16x32_bf16 v[4:7], v[172:175], v[212:215], v[4:7]
	v_mfma_f32_16x16x32_bf16 v[0:3], v[176:179], v[208:211], v[0:3]
	v_mfma_f32_16x16x32_bf16 v[0:3], v[180:183], v[212:215], v[0:3]
	s_setprio 0
	s_barrier
	s_add_i32 s75, 0, 0x18000
	s_add_i32 s76, 0, 0x1c000
	v_add_u32_e32 v164, s75, v151
	v_add_u32_e32 v180, s76, v151
	ds_read_b128 v[144:147], v164
	ds_read_b128 v[156:159], v164 offset:1024
	ds_read_b128 v[160:163], v164 offset:2048
	ds_read_b128 v[164:167], v164 offset:3072
	ds_read_b128 v[168:171], v180
	ds_read_b128 v[172:175], v180 offset:1024
	ds_read_b128 v[176:179], v180 offset:2048
	ds_read_b128 v[180:183], v180 offset:3072
	s_add_u32 s40, s40, 0x20000
	s_addc_u32 s41, s41, 0
	s_mov_b32 m0, s53
	v_lshl_add_u64 v[222:223], s[40:41], 0, v[134:135]
	ds_read_b128 v[184:187], v155 offset:32768
	ds_read_b128 v[188:191], v155 offset:33792
	ds_read_b128 v[192:195], v155 offset:34816
	ds_read_b128 v[196:199], v155 offset:35840
	ds_read_b128 v[200:203], v155 offset:36864
	ds_read_b128 v[204:207], v155 offset:37888
	ds_read_b128 v[208:211], v155 offset:38912
	ds_read_b128 v[212:215], v155 offset:39936
	global_load_lds_dwordx4 v[222:223], off
	v_lshl_add_u64 v[222:223], s[40:41], 0, v[130:131]
	s_mov_b32 m0, s60
	s_nop 0
	global_load_lds_dwordx4 v[222:223], off
	s_waitcnt vmcnt(8)
	s_waitcnt lgkmcnt(0)
	s_barrier
	s_setprio 1
	s_waitcnt lgkmcnt(0)
	v_mfma_f32_16x16x32_bf16 v[124:127], v[144:147], v[184:187], v[124:127]
	v_mfma_f32_16x16x32_bf16 v[124:127], v[156:159], v[188:191], v[124:127]
	v_mfma_f32_16x16x32_bf16 v[120:123], v[160:163], v[184:187], v[120:123]
	v_mfma_f32_16x16x32_bf16 v[120:123], v[164:167], v[188:191], v[120:123]
	v_mfma_f32_16x16x32_bf16 v[112:115], v[144:147], v[192:195], v[112:115]
	v_mfma_f32_16x16x32_bf16 v[112:115], v[156:159], v[196:199], v[112:115]
	v_mfma_f32_16x16x32_bf16 v[104:107], v[160:163], v[192:195], v[104:107]
	v_mfma_f32_16x16x32_bf16 v[104:107], v[164:167], v[196:199], v[104:107]
	v_mfma_f32_16x16x32_bf16 v[96:99], v[144:147], v[200:203], v[96:99]
	v_mfma_f32_16x16x32_bf16 v[96:99], v[156:159], v[204:207], v[96:99]
	v_mfma_f32_16x16x32_bf16 v[88:91], v[160:163], v[200:203], v[88:91]
	v_mfma_f32_16x16x32_bf16 v[88:91], v[164:167], v[204:207], v[88:91]
	v_mfma_f32_16x16x32_bf16 v[80:83], v[144:147], v[208:211], v[80:83]
	v_mfma_f32_16x16x32_bf16 v[80:83], v[156:159], v[212:215], v[80:83]
	v_mfma_f32_16x16x32_bf16 v[72:75], v[160:163], v[208:211], v[72:75]
	v_mfma_f32_16x16x32_bf16 v[72:75], v[164:167], v[212:215], v[72:75]
	s_setprio 0
	s_setprio 1
	v_mfma_f32_16x16x32_bf16 v[116:119], v[168:171], v[184:187], v[116:119]
	v_mfma_f32_16x16x32_bf16 v[116:119], v[172:175], v[188:191], v[116:119]
	v_mfma_f32_16x16x32_bf16 v[108:111], v[176:179], v[184:187], v[108:111]
	v_mfma_f32_16x16x32_bf16 v[108:111], v[180:183], v[188:191], v[108:111]
	v_mfma_f32_16x16x32_bf16 v[100:103], v[168:171], v[192:195], v[100:103]
	v_mfma_f32_16x16x32_bf16 v[100:103], v[172:175], v[196:199], v[100:103]
	v_mfma_f32_16x16x32_bf16 v[92:95], v[176:179], v[192:195], v[92:95]
	v_mfma_f32_16x16x32_bf16 v[92:95], v[180:183], v[196:199], v[92:95]
	v_mfma_f32_16x16x32_bf16 v[84:87], v[168:171], v[200:203], v[84:87]
	v_mfma_f32_16x16x32_bf16 v[84:87], v[172:175], v[204:207], v[84:87]
	v_mfma_f32_16x16x32_bf16 v[76:79], v[176:179], v[200:203], v[76:79]
	v_mfma_f32_16x16x32_bf16 v[76:79], v[180:183], v[204:207], v[76:79]
	v_mfma_f32_16x16x32_bf16 v[68:71], v[168:171], v[208:211], v[68:71]
	v_mfma_f32_16x16x32_bf16 v[68:71], v[172:175], v[212:215], v[68:71]
	v_mfma_f32_16x16x32_bf16 v[64:67], v[176:179], v[208:211], v[64:67]
	v_mfma_f32_16x16x32_bf16 v[64:67], v[180:183], v[212:215], v[64:67]
	s_setprio 0
	s_barrier
; #define PG8_STAGE(bufoff, gbase, voff) do { _Pragma("unroll") for (int _i = 0; _i < 2; ++_i) \
;         __builtin_amdgcn_global_load_lds((const unsigned*)((const char*)(gbase) + (voff)[_i]), (PG8_LAS unsigned*)(lds + (bufoff) + ldsw + _i * 8192), 16, 0, 0); } while (0)
; #define PG8_LDA(dst, b, h) do { _Pragma("unroll") for (int m = 0; m < 4; ++m) _Pragma("unroll") for (int k = 0; k < 2; ++k) dst[m][k] = *(const PG8_LAS bf16x8*)(lds + PG8_SA(b, h) + aoff + m * 2048 + k * 1024); } while (0)
; #define PG8_LDB(dst, b, h) do { _Pragma("unroll") for (int n = 0; n < 2; ++n) _Pragma("unroll") for (int k = 0; k < 2; ++k) dst[n][k] = *(const PG8_LAS bf16x8*)(lds + PG8_SB(b, h) + boff + n * 2048 + k * 1024); } while (0)
; template <class Epi, class Sched, bool ALIGN_EPI = false, bool SP2 = false>
; __device__ __forceinline__ void gemm_phase(PG8_LAS unsigned char* lds, const Gemm g, const Sched& S, const Epi& E) {
;     ...
;         for (int t = 0; t < nt; t += 2) {
;             const bool last = (t == nt - 2);
;             const char* a1 = cA + (size_t)(t + 1) * kstep;
;             const char* a2 = last ? nA : cA + (size_t)(t + 2) * kstep; const char* b2 = last ? nB : cB + (size_t)(t + 2) * kstep;
;             const char* a3 = a2 + kstep; const char* b3 = b2 + kstep;
;             if (last && has_next) S.a_ready(nxt);
;             if constexpr (SP2) {
;             PG8_LDB(B0, 0, 0); PG8_LDB(B1, 0, 1); PG8_SCHED; PG8_LDA(At, 0, 0); PG8_STAGE(PG8_SA(1, 1), a1 + hstep, voffA);
;             PG8_WAIT_V(8); PG8_WAIT_L(0); PG8_BAR; PG8_MMA(0, 0, At, B0); PG8_MMA(0, 1, At, B1); PG8_BAR; PG8_SCHED;
;             PG8_LDA(At, 0, 1); PG8_STAGE(PG8_SB(0, 0), b2, voffB); PG8_STAGE(PG8_SB(0, 1), b2 + hstep, voffB); PG8_STAGE(PG8_SA(0, 0), a2, voffA);
;             PG8_WAIT_V(8); PG8_WAIT_L(0); PG8_BAR; PG8_MMA(1, 0, At, B0); PG8_MMA(1, 1, At, B1); PG8_BAR; PG8_SCHED;
;             PG8_LDB(B0, 1, 0); PG8_LDB(B1, 1, 1); PG8_SCHED; PG8_LDA(At, 1, 0); PG8_STAGE(PG8_SA(0, 1), a2 + hstep, voffA);
;             PG8_WAIT_V(8); PG8_WAIT_L(0); PG8_BAR; PG8_MMA(0, 0, At, B0); PG8_MMA(0, 1, At, B1); PG8_BAR; PG8_SCHED;
;             PG8_LDA(At, 1, 1); PG8_STAGE(PG8_SB(1, 0), b3, voffB); PG8_STAGE(PG8_SB(1, 1), b3 + hstep, voffB); PG8_STAGE(PG8_SA(1, 0), a3, voffA);
;             PG8_WAIT_V(8); PG8_WAIT_L(0); PG8_BAR; PG8_MMA(1, 0, At, B0); PG8_MMA(1, 1, At, B1); PG8_BAR; PG8_SCHED;
	s_add_i32 s40, s75, s43
	v_lshl_add_u64 v[148:149], v[148:149], 0, s[12:13]
	s_mov_b32 m0, s40
	ds_read_b128 v[184:187], v155 offset:49152
	ds_read_b128 v[188:191], v155 offset:50176
	ds_read_b128 v[192:195], v155 offset:51200
	ds_read_b128 v[196:199], v155 offset:52224
	ds_read_b128 v[200:203], v155 offset:53248
	ds_read_b128 v[204:207], v155 offset:54272
	ds_read_b128 v[208:211], v155 offset:55296
	ds_read_b128 v[212:215], v155 offset:56320
	global_load_lds_dwordx4 v[148:149], off
	s_add_i32 m0, s40, 0x2000
	s_add_u32 s38, s38, 0x20080
	v_lshl_add_u64 v[148:149], v[216:217], 0, s[12:13]
	s_addc_u32 s39, s39, 0
	s_add_i32 s40, s76, s43
	global_load_lds_dwordx4 v[148:149], off
	v_lshl_add_u64 v[148:149], s[38:39], 0, v[132:133]
	s_mov_b32 m0, s40
	s_nop 0
	global_load_lds_dwordx4 v[148:149], off
	v_lshl_add_u64 v[148:149], s[38:39], 0, v[128:129]
	s_add_i32 m0, s40, 0x2000
	s_nop 0
	global_load_lds_dwordx4 v[148:149], off
	v_lshl_add_u64 v[148:149], v[218:219], 0, s[12:13]
	s_mov_b32 m0, s64
	s_nop 0
	global_load_lds_dwordx4 v[148:149], off
	v_lshl_add_u64 v[148:149], v[220:221], 0, s[12:13]
	s_mov_b32 m0, s65
	s_nop 0
	global_load_lds_dwordx4 v[148:149], off
	s_waitcnt vmcnt(8)
	s_waitcnt lgkmcnt(0)
	s_barrier
	s_setprio 1
	s_waitcnt lgkmcnt(0)
	v_mfma_f32_16x16x32_bf16 v[60:63], v[144:147], v[184:187], v[60:63]
	v_mfma_f32_16x16x32_bf16 v[60:63], v[156:159], v[188:191], v[60:63]
	v_mfma_f32_16x16x32_bf16 v[56:59], v[160:163], v[184:187], v[56:59]
	v_mfma_f32_16x16x32_bf16 v[56:59], v[164:167], v[188:191], v[56:59]
	v_mfma_f32_16x16x32_bf16 v[48:51], v[144:147], v[192:195], v[48:51]
	v_mfma_f32_16x16x32_bf16 v[48:51], v[156:159], v[196:199], v[48:51]
	v_mfma_f32_16x16x32_bf16 v[40:43], v[160:163], v[192:195], v[40:43]
	v_mfma_f32_16x16x32_bf16 v[40:43], v[164:167], v[196:199], v[40:43]
	v_mfma_f32_16x16x32_bf16 v[32:35], v[144:147], v[200:203], v[32:35]
	v_mfma_f32_16x16x32_bf16 v[32:35], v[156:159], v[204:207], v[32:35]
	v_mfma_f32_16x16x32_bf16 v[24:27], v[160:163], v[200:203], v[24:27]
	v_mfma_f32_16x16x32_bf16 v[24:27], v[164:167], v[204:207], v[24:27]
	v_mfma_f32_16x16x32_bf16 v[16:19], v[144:147], v[208:211], v[16:19]
	v_mfma_f32_16x16x32_bf16 v[16:19], v[156:159], v[212:215], v[16:19]
	v_mfma_f32_16x16x32_bf16 v[8:11], v[160:163], v[208:211], v[8:11]
	v_mfma_f32_16x16x32_bf16 v[8:11], v[164:167], v[212:215], v[8:11]
	s_setprio 0
	s_setprio 1
	v_mfma_f32_16x16x32_bf16 v[52:55], v[168:171], v[184:187], v[52:55]
	v_mfma_f32_16x16x32_bf16 v[52:55], v[172:175], v[188:191], v[52:55]
	v_mfma_f32_16x16x32_bf16 v[44:47], v[176:179], v[184:187], v[44:47]
	v_mfma_f32_16x16x32_bf16 v[44:47], v[180:183], v[188:191], v[44:47]
	v_mfma_f32_16x16x32_bf16 v[36:39], v[168:171], v[192:195], v[36:39]
	v_mfma_f32_16x16x32_bf16 v[36:39], v[172:175], v[196:199], v[36:39]
	v_mfma_f32_16x16x32_bf16 v[28:31], v[176:179], v[192:195], v[28:31]
	v_mfma_f32_16x16x32_bf16 v[28:31], v[180:183], v[196:199], v[28:31]
	v_mfma_f32_16x16x32_bf16 v[20:23], v[168:171], v[200:203], v[20:23]
	v_mfma_f32_16x16x32_bf16 v[20:23], v[172:175], v[204:207], v[20:23]
	v_mfma_f32_16x16x32_bf16 v[12:15], v[176:179], v[200:203], v[12:15]
	v_mfma_f32_16x16x32_bf16 v[12:15], v[180:183], v[204:207], v[12:15]
	v_mfma_f32_16x16x32_bf16 v[4:7], v[168:171], v[208:211], v[4:7]
	v_mfma_f32_16x16x32_bf16 v[4:7], v[172:175], v[212:215], v[4:7]
	v_mfma_f32_16x16x32_bf16 v[0:3], v[176:179], v[208:211], v[0:3]
	v_mfma_f32_16x16x32_bf16 v[0:3], v[180:183], v[212:215], v[0:3]
	s_setprio 0
	s_barrier
	s_mov_b32 s99, 0
	s_add_i32 s74, s74, 2
	s_add_u32 s36, s36, 0x100
	s_addc_u32 s37, s37, 0
	s_add_u32 s72, s72, 0x100
	s_addc_u32 s73, s73, 0
	s_cmp_gt_u32 s74, 5
	s_cbranch_scc0 .LBB0_1284
	s_and_b64 vcc, exec, s[14:15]
	s_cbranch_vccz .LBB0_1287
	s_barrier

; #define PG8_STAGE(bufoff, gbase, voff) do { _Pragma("unroll") for (int _i = 0; _i < 2; ++_i) \
;         __builtin_amdgcn_global_load_lds((const unsigned*)((const char*)(gbase) + (voff)[_i]), (PG8_LAS unsigned*)(lds + (bufoff) + ldsw + _i * 8192), 16, 0, 0); } while (0)
; #define PG8_LDA(dst, b, h) do { _Pragma("unroll") for (int m = 0; m < 4; ++m) _Pragma("unroll") for (int k = 0; k < 2; ++k) dst[m][k] = *(const PG8_LAS bf16x8*)(lds + PG8_SA(b, h) + aoff + m * 2048 + k * 1024); } while (0)
; #define PG8_LDB(dst, b, h) do { _Pragma("unroll") for (int n = 0; n < 2; ++n) _Pragma("unroll") for (int k = 0; k < 2; ++k) dst[n][k] = *(const PG8_LAS bf16x8*)(lds + PG8_SB(b, h) + boff + n * 2048 + k * 1024); } while (0)
; #define PG8_WAIT_V(n) asm volatile("s_waitcnt vmcnt(" #n ")" ::: "memory")
; #define PG8_BAR __builtin_amdgcn_s_barrier()
; template <class Epi, class Sched, bool ALIGN_EPI = false, bool SP2 = false>
; __device__ __forceinline__ void gemm_phase(PG8_LAS unsigned char* lds, const Gemm g, const Sched& S, const Epi& E) {
;     ...
;     f32x4 acc[2][2][4][2];
; #pragma unroll
;     for (int a = 0; a < 2; ++a)
; #pragma unroll
;         for (int b = 0; b < 2; ++b)
; #pragma unroll
;             for (int m = 0; m < 4; ++m)
; #pragma unroll
;                 for (int n = 0; n < 2; ++n) acc[a][b][m][n] = (f32x4){0.f, 0.f, 0.f, 0.f};
;     ...
;             PG8_LDB(B0, 0, 0); PG8_LDB(B1, 0, 1); PG8_SCHED; PG8_LDA(At, 0, 0); PG8_STAGE(PG8_SA(1, 1), a1 + hstep, voffA);
;             PG8_WAIT_V(8); PG8_WAIT_L(0); PG8_BAR; PG8_MMA(0, 0, At, B0); PG8_MMA(0, 1, At, B1); PG8_BAR; PG8_SCHED;
;             PG8_LDA(At, 0, 1); PG8_STAGE(PG8_SB(0, 0), b2, voffB); PG8_STAGE(PG8_SB(0, 1), b2 + hstep, voffB); PG8_STAGE(PG8_SA(0, 0), a2, voffA);
;             PG8_WAIT_V(8); PG8_WAIT_L(0); PG8_BAR; PG8_MMA(1, 0, At, B0); PG8_MMA(1, 1, At, B1); PG8_BAR; PG8_SCHED;
;             PG8_LDB(B0, 1, 0); PG8_LDB(B1, 1, 1); PG8_SCHED; PG8_LDA(At, 1, 0); PG8_STAGE(PG8_SA(0, 1), a2 + hstep, voffA);
;             PG8_WAIT_V(8); PG8_WAIT_L(0); PG8_BAR; PG8_MMA(0, 0, At, B0); PG8_MMA(0, 1, At, B1); PG8_BAR; PG8_SCHED;
;             PG8_LDA(At, 1, 1); PG8_STAGE(PG8_SB(1, 0), b3, voffB); PG8_STAGE(PG8_SB(1, 1), b3 + hstep, voffB); PG8_STAGE(PG8_SA(1, 0), a3, voffA);
;             PG8_WAIT_V(8); PG8_WAIT_L(0); PG8_BAR; PG8_MMA(1, 0, At, B0); PG8_MMA(1, 1, At, B1); PG8_BAR; PG8_SCHED;
.Lrj_P3b_1:
	s_mov_b32 s99, 0
	s_waitcnt lgkmcnt(0)
	s_barrier
	s_setprio 1
	s_waitcnt lgkmcnt(0)
	v_mfma_f32_16x16x32_bf16 v[140:143], v[0:3], v[60:63], 0
	v_mfma_f32_16x16x32_bf16 v[158:161], v[0:3], v[104:107], 0
	v_mfma_f32_16x16x32_bf16 v[166:169], v[0:3], v[112:115], 0
	v_mfma_f32_16x16x32_bf16 v[0:3], v[0:3], v[120:123], 0
	v_mfma_f32_16x16x32_bf16 v[140:143], v[4:7], v[100:103], v[140:143]
	v_mfma_f32_16x16x32_bf16 v[158:161], v[4:7], v[108:111], v[158:161]
	v_mfma_f32_16x16x32_bf16 v[166:169], v[4:7], v[116:119], v[166:169]
	v_mfma_f32_16x16x32_bf16 v[0:3], v[4:7], v[124:127], v[0:3]
	v_mfma_f32_16x16x32_bf16 v[4:7], v[8:11], v[120:123], 0
	v_mfma_f32_16x16x32_bf16 v[154:157], v[8:11], v[60:63], 0
	v_mfma_f32_16x16x32_bf16 v[162:165], v[8:11], v[104:107], 0
	v_mfma_f32_16x16x32_bf16 v[170:173], v[8:11], v[112:115], 0
	v_mfma_f32_16x16x32_bf16 v[4:7], v[12:15], v[124:127], v[4:7]
	v_mfma_f32_16x16x32_bf16 v[154:157], v[12:15], v[100:103], v[154:157]
	v_mfma_f32_16x16x32_bf16 v[162:165], v[12:15], v[108:111], v[162:165]
	v_mfma_f32_16x16x32_bf16 v[170:173], v[12:15], v[116:119], v[170:173]
	s_setprio 0
	s_setprio 1
	v_mfma_f32_16x16x32_bf16 v[8:11], v[16:19], v[60:63], 0
	v_mfma_f32_16x16x32_bf16 v[12:15], v[24:27], v[60:63], 0
	v_mfma_f32_16x16x32_bf16 v[8:11], v[20:23], v[100:103], v[8:11]
	v_mfma_f32_16x16x32_bf16 v[12:15], v[28:31], v[100:103], v[12:15]
	v_mfma_f32_16x16x32_bf16 v[60:63], v[16:19], v[104:107], 0
	v_mfma_f32_16x16x32_bf16 v[100:103], v[24:27], v[104:107], 0
	v_mfma_f32_16x16x32_bf16 v[104:107], v[16:19], v[112:115], 0
	v_mfma_f32_16x16x32_bf16 v[16:19], v[16:19], v[120:123], 0
	v_mfma_f32_16x16x32_bf16 v[60:63], v[20:23], v[108:111], v[60:63]
	v_mfma_f32_16x16x32_bf16 v[100:103], v[28:31], v[108:111], v[100:103]
	v_mfma_f32_16x16x32_bf16 v[104:107], v[20:23], v[116:119], v[104:107]
	v_mfma_f32_16x16x32_bf16 v[108:111], v[24:27], v[112:115], 0
	v_mfma_f32_16x16x32_bf16 v[16:19], v[20:23], v[124:127], v[16:19]
	v_mfma_f32_16x16x32_bf16 v[20:23], v[24:27], v[120:123], 0
	v_mfma_f32_16x16x32_bf16 v[108:111], v[28:31], v[116:119], v[108:111]
	v_mfma_f32_16x16x32_bf16 v[20:23], v[28:31], v[124:127], v[20:23]
	s_setprio 0
	s_barrier
	s_add_i32 s37, 0, 0x1c000
	v_add_u32_e32 v153, s37, v147
	ds_read_b128 v[24:27], v152
	ds_read_b128 v[28:31], v152 offset:1024
	ds_read_b128 v[112:115], v152 offset:2048
	ds_read_b128 v[116:119], v152 offset:3072
	ds_read_b128 v[120:123], v153
	ds_read_b128 v[124:127], v153 offset:1024
	ds_read_b128 v[174:177], v153 offset:2048
	ds_read_b128 v[178:181], v153 offset:3072
	s_add_u32 s88, s52, 0x10100
	s_addc_u32 s89, s53, 0
	s_mov_b32 m0, s68
	v_lshl_add_u64 v[220:221], s[88:89], 0, v[134:135]
	ds_read_b128 v[182:185], v151 offset:32768
	ds_read_b128 v[186:189], v151 offset:33792
	ds_read_b128 v[190:193], v151 offset:34816
	ds_read_b128 v[194:197], v151 offset:35840
	ds_read_b128 v[198:201], v151 offset:36864
	ds_read_b128 v[202:205], v151 offset:37888
	ds_read_b128 v[206:209], v151 offset:38912
	ds_read_b128 v[210:213], v151 offset:39936
	global_load_lds_dwordx4 v[220:221], off
	v_lshl_add_u64 v[220:221], s[88:89], 0, v[130:131]
	s_mov_b32 m0, s69
	s_nop 0
	global_load_lds_dwordx4 v[220:221], off
	s_waitcnt vmcnt(8)
	s_waitcnt lgkmcnt(0)
	s_barrier
	s_setprio 1
	s_waitcnt lgkmcnt(0)
	v_mfma_f32_16x16x32_bf16 v[64:67], v[24:27], v[182:185], v[64:67]
	v_mfma_f32_16x16x32_bf16 v[64:67], v[28:31], v[186:189], v[64:67]
	v_mfma_f32_16x16x32_bf16 v[68:71], v[112:115], v[182:185], v[68:71]
	v_mfma_f32_16x16x32_bf16 v[68:71], v[116:119], v[186:189], v[68:71]
	v_mfma_f32_16x16x32_bf16 v[72:75], v[24:27], v[190:193], v[72:75]
	v_mfma_f32_16x16x32_bf16 v[72:75], v[28:31], v[194:197], v[72:75]
	v_mfma_f32_16x16x32_bf16 v[76:79], v[112:115], v[190:193], v[76:79]
	v_mfma_f32_16x16x32_bf16 v[76:79], v[116:119], v[194:197], v[76:79]
	v_mfma_f32_16x16x32_bf16 v[80:83], v[24:27], v[198:201], v[80:83]
	v_mfma_f32_16x16x32_bf16 v[80:83], v[28:31], v[202:205], v[80:83]
	v_mfma_f32_16x16x32_bf16 v[84:87], v[112:115], v[198:201], v[84:87]
	v_mfma_f32_16x16x32_bf16 v[84:87], v[116:119], v[202:205], v[84:87]
	v_mfma_f32_16x16x32_bf16 v[88:91], v[24:27], v[206:209], v[88:91]
	v_mfma_f32_16x16x32_bf16 v[88:91], v[28:31], v[210:213], v[88:91]
	v_mfma_f32_16x16x32_bf16 v[92:95], v[112:115], v[206:209], v[92:95]
	v_mfma_f32_16x16x32_bf16 v[92:95], v[116:119], v[210:213], v[92:95]
	s_setprio 0
	s_setprio 1
	v_mfma_f32_16x16x32_bf16 v[96:99], v[120:123], v[182:185], v[96:99]
	v_mfma_f32_16x16x32_bf16 v[96:99], v[124:127], v[186:189], v[96:99]
	v_mfma_f32_16x16x32_bf16 v[32:35], v[174:177], v[182:185], v[32:35]
	v_mfma_f32_16x16x32_bf16 v[32:35], v[178:181], v[186:189], v[32:35]
	v_mfma_f32_16x16x32_bf16 v[36:39], v[120:123], v[190:193], v[36:39]
	v_mfma_f32_16x16x32_bf16 v[36:39], v[124:127], v[194:197], v[36:39]
	v_mfma_f32_16x16x32_bf16 v[40:43], v[174:177], v[190:193], v[40:43]
	v_mfma_f32_16x16x32_bf16 v[40:43], v[178:181], v[194:197], v[40:43]
	v_mfma_f32_16x16x32_bf16 v[44:47], v[120:123], v[198:201], v[44:47]
	v_mfma_f32_16x16x32_bf16 v[44:47], v[124:127], v[202:205], v[44:47]
	v_mfma_f32_16x16x32_bf16 v[48:51], v[174:177], v[198:201], v[48:51]
	v_mfma_f32_16x16x32_bf16 v[48:51], v[178:181], v[202:205], v[48:51]
	v_mfma_f32_16x16x32_bf16 v[52:55], v[120:123], v[206:209], v[52:55]
	v_mfma_f32_16x16x32_bf16 v[52:55], v[124:127], v[210:213], v[52:55]
	v_mfma_f32_16x16x32_bf16 v[56:59], v[174:177], v[206:209], v[56:59]
	v_mfma_f32_16x16x32_bf16 v[56:59], v[178:181], v[210:213], v[56:59]
	s_setprio 0
	s_barrier
; #define PG8_STAGE(bufoff, gbase, voff) do { _Pragma("unroll") for (int _i = 0; _i < 2; ++_i) \
;         __builtin_amdgcn_global_load_lds((const unsigned*)((const char*)(gbase) + (voff)[_i]), (PG8_LAS unsigned*)(lds + (bufoff) + ldsw + _i * 8192), 16, 0, 0); } while (0)
; #define PG8_LDA(dst, b, h) do { _Pragma("unroll") for (int m = 0; m < 4; ++m) _Pragma("unroll") for (int k = 0; k < 2; ++k) dst[m][k] = *(const PG8_LAS bf16x8*)(lds + PG8_SA(b, h) + aoff + m * 2048 + k * 1024); } while (0)
; #define PG8_LDB(dst, b, h) do { _Pragma("unroll") for (int n = 0; n < 2; ++n) _Pragma("unroll") for (int k = 0; k < 2; ++k) dst[n][k] = *(const PG8_LAS bf16x8*)(lds + PG8_SB(b, h) + boff + n * 2048 + k * 1024); } while (0)
; #define PG8_MMA(ai, bj, At, Bt) do { __builtin_amdgcn_s_setprio(1); _Pragma("unroll") for (int m = 0; m < 4; ++m) _Pragma("unroll") for (int n = 0; n < 2; ++n) _Pragma("unroll") for (int k = 0; k < 2; ++k) \
;         acc[ai][bj][m][n] = __builtin_amdgcn_mfma_f32_16x16x32_bf16(Bt[n][k], At[m][k], acc[ai][bj][m][n], 0, 0, 0); __builtin_amdgcn_s_setprio(0); } while (0)
; #define PG8_WAIT_V(n) asm volatile("s_waitcnt vmcnt(" #n ")" ::: "memory")
; template <class Epi, class Sched, bool ALIGN_EPI = false, bool SP2 = false>
; __device__ __forceinline__ void gemm_phase(PG8_LAS unsigned char* lds, const Gemm g, const Sched& S, const Epi& E) {
;     ...
;             PG8_LDB(B0, 0, 0); PG8_LDB(B1, 0, 1); PG8_SCHED; PG8_LDA(At, 0, 0); PG8_STAGE(PG8_SA(1, 1), a1 + hstep, voffA);
;             PG8_WAIT_V(8); PG8_WAIT_L(0); PG8_BAR; PG8_MMA(0, 0, At, B0); PG8_MMA(0, 1, At, B1); PG8_BAR; PG8_SCHED;
;             PG8_LDA(At, 0, 1); PG8_STAGE(PG8_SB(0, 0), b2, voffB); PG8_STAGE(PG8_SB(0, 1), b2 + hstep, voffB); PG8_STAGE(PG8_SA(0, 0), a2, voffA);
;             PG8_WAIT_V(8); PG8_WAIT_L(0); PG8_BAR; PG8_MMA(1, 0, At, B0); PG8_MMA(1, 1, At, B1); PG8_BAR; PG8_SCHED;
;             PG8_LDB(B0, 1, 0); PG8_LDB(B1, 1, 1); PG8_SCHED; PG8_LDA(At, 1, 0); PG8_STAGE(PG8_SA(0, 1), a2 + hstep, voffA);
;             PG8_WAIT_V(8); PG8_WAIT_L(0); PG8_BAR; PG8_MMA(0, 0, At, B0); PG8_MMA(0, 1, At, B1); PG8_BAR; PG8_SCHED;
;             PG8_LDA(At, 1, 1); PG8_STAGE(PG8_SB(1, 0), b3, voffB); PG8_STAGE(PG8_SB(1, 1), b3 + hstep, voffB); PG8_STAGE(PG8_SA(1, 0), a3, voffA);
;             PG8_WAIT_V(8); PG8_WAIT_L(0); PG8_BAR; PG8_MMA(1, 0, At, B0); PG8_MMA(1, 1, At, B1); PG8_BAR; PG8_SCHED;
	s_add_i32 s83, s81, s47
	s_add_i32 s35, s83, 0x2000
	v_lshl_add_u64 v[144:145], v[144:145], 0, s[22:23]
	s_mov_b32 m0, s83
	s_add_u32 s62, s62, 0x10180
	ds_read_b128 v[182:185], v151 offset:49152
	ds_read_b128 v[186:189], v151 offset:50176
	ds_read_b128 v[190:193], v151 offset:51200
	ds_read_b128 v[194:197], v151 offset:52224
	ds_read_b128 v[198:201], v151 offset:53248
	ds_read_b128 v[202:205], v151 offset:54272
	ds_read_b128 v[206:209], v151 offset:55296
	ds_read_b128 v[210:213], v151 offset:56320
	global_load_lds_dwordx4 v[144:145], off
	v_lshl_add_u64 v[144:145], v[214:215], 0, s[22:23]
	s_mov_b32 m0, s35
	s_addc_u32 s63, s63, 0
	s_add_i32 s37, s37, s47
	global_load_lds_dwordx4 v[144:145], off
	v_lshl_add_u64 v[144:145], s[62:63], 0, v[132:133]
	s_mov_b32 m0, s37
	s_nop 0
	global_load_lds_dwordx4 v[144:145], off
	v_lshl_add_u64 v[144:145], s[62:63], 0, v[128:129]
	s_add_i32 s62, s37, 0x2000
	s_mov_b32 m0, s62
	s_nop 0
	global_load_lds_dwordx4 v[144:145], off
	v_lshl_add_u64 v[144:145], v[216:217], 0, s[22:23]
	s_mov_b32 m0, s70
	s_nop 0
	global_load_lds_dwordx4 v[144:145], off
	v_lshl_add_u64 v[144:145], v[218:219], 0, s[22:23]
	s_mov_b32 m0, s71
	s_nop 0
	global_load_lds_dwordx4 v[144:145], off
	s_waitcnt vmcnt(8)
	s_waitcnt lgkmcnt(0)
	s_barrier
	s_setprio 1
	s_waitcnt lgkmcnt(0)
	v_mfma_f32_16x16x32_bf16 v[0:3], v[24:27], v[206:209], v[0:3]
	v_mfma_f32_16x16x32_bf16 v[0:3], v[28:31], v[210:213], v[0:3]
	v_mfma_f32_16x16x32_bf16 v[4:7], v[112:115], v[206:209], v[4:7]
	v_mfma_f32_16x16x32_bf16 v[4:7], v[116:119], v[210:213], v[4:7]
	v_mfma_f32_16x16x32_bf16 v[140:143], v[24:27], v[182:185], v[140:143]
	v_mfma_f32_16x16x32_bf16 v[140:143], v[28:31], v[186:189], v[140:143]
	v_mfma_f32_16x16x32_bf16 v[154:157], v[112:115], v[182:185], v[154:157]
	v_mfma_f32_16x16x32_bf16 v[154:157], v[116:119], v[186:189], v[154:157]
	v_mfma_f32_16x16x32_bf16 v[158:161], v[24:27], v[190:193], v[158:161]
	v_mfma_f32_16x16x32_bf16 v[158:161], v[28:31], v[194:197], v[158:161]
	v_mfma_f32_16x16x32_bf16 v[162:165], v[112:115], v[190:193], v[162:165]
	v_mfma_f32_16x16x32_bf16 v[162:165], v[116:119], v[194:197], v[162:165]
	v_mfma_f32_16x16x32_bf16 v[166:169], v[24:27], v[198:201], v[166:169]
	v_mfma_f32_16x16x32_bf16 v[166:169], v[28:31], v[202:205], v[166:169]
	v_mfma_f32_16x16x32_bf16 v[170:173], v[112:115], v[198:201], v[170:173]
	v_mfma_f32_16x16x32_bf16 v[170:173], v[116:119], v[202:205], v[170:173]
	s_setprio 0
	s_setprio 1
	v_mfma_f32_16x16x32_bf16 v[8:11], v[120:123], v[182:185], v[8:11]
	v_mfma_f32_16x16x32_bf16 v[12:15], v[174:177], v[182:185], v[12:15]
	v_mfma_f32_16x16x32_bf16 v[24:27], v[120:123], v[190:193], v[60:63]
	v_mfma_f32_16x16x32_bf16 v[28:31], v[174:177], v[190:193], v[100:103]
	v_mfma_f32_16x16x32_bf16 v[60:63], v[120:123], v[198:201], v[104:107]
	v_mfma_f32_16x16x32_bf16 v[100:103], v[174:177], v[198:201], v[108:111]
	v_mfma_f32_16x16x32_bf16 v[16:19], v[120:123], v[206:209], v[16:19]
	v_mfma_f32_16x16x32_bf16 v[20:23], v[174:177], v[206:209], v[20:23]
	v_mfma_f32_16x16x32_bf16 v[8:11], v[124:127], v[186:189], v[8:11]
	v_mfma_f32_16x16x32_bf16 v[12:15], v[178:181], v[186:189], v[12:15]
	v_mfma_f32_16x16x32_bf16 v[24:27], v[124:127], v[194:197], v[24:27]
	v_mfma_f32_16x16x32_bf16 v[28:31], v[178:181], v[194:197], v[28:31]
	v_mfma_f32_16x16x32_bf16 v[60:63], v[124:127], v[202:205], v[60:63]
	v_mfma_f32_16x16x32_bf16 v[100:103], v[178:181], v[202:205], v[100:103]
	v_mfma_f32_16x16x32_bf16 v[16:19], v[124:127], v[210:213], v[16:19]
	v_mfma_f32_16x16x32_bf16 v[20:23], v[178:181], v[210:213], v[20:23]
	s_setprio 0
	s_barrier
	ds_read_b128 v[104:107], v149
	ds_read_b128 v[108:111], v149 offset:1024
	ds_read_b128 v[112:115], v149 offset:2048
	ds_read_b128 v[116:119], v149 offset:3072
	ds_read_b128 v[120:123], v150
	ds_read_b128 v[124:127], v150 offset:1024
	ds_read_b128 v[174:177], v150 offset:2048
	ds_read_b128 v[178:181], v150 offset:3072
	s_add_u32 s52, s52, 0x10180
	s_addc_u32 s53, s53, 0
	s_mov_b32 m0, s73
	v_lshl_add_u64 v[144:145], s[52:53], 0, v[134:135]
	ds_read_b128 v[182:185], v151
	ds_read_b128 v[186:189], v151 offset:1024
	ds_read_b128 v[190:193], v151 offset:2048
	ds_read_b128 v[194:197], v151 offset:3072
	ds_read_b128 v[198:201], v151 offset:4096
	ds_read_b128 v[202:205], v151 offset:5120
	ds_read_b128 v[206:209], v151 offset:6144
	ds_read_b128 v[210:213], v151 offset:7168
	global_load_lds_dwordx4 v[144:145], off
	v_lshl_add_u64 v[144:145], s[52:53], 0, v[130:131]
	s_mov_b32 m0, s74
	s_nop 0
	global_load_lds_dwordx4 v[144:145], off
	s_waitcnt vmcnt(8)
	s_waitcnt lgkmcnt(0)
	s_barrier
; #define PG8_STAGE(bufoff, gbase, voff) do { _Pragma("unroll") for (int _i = 0; _i < 2; ++_i) \
;         __builtin_amdgcn_global_load_lds((const unsigned*)((const char*)(gbase) + (voff)[_i]), (PG8_LAS unsigned*)(lds + (bufoff) + ldsw + _i * 8192), 16, 0, 0); } while (0)
; #define PG8_LDA(dst, b, h) do { _Pragma("unroll") for (int m = 0; m < 4; ++m) _Pragma("unroll") for (int k = 0; k < 2; ++k) dst[m][k] = *(const PG8_LAS bf16x8*)(lds + PG8_SA(b, h) + aoff + m * 2048 + k * 1024); } while (0)
; #define PG8_WAIT_V(n) asm volatile("s_waitcnt vmcnt(" #n ")" ::: "memory")
; template <class Epi, class Sched, bool ALIGN_EPI = false, bool SP2 = false>
; __device__ __forceinline__ void gemm_phase(PG8_LAS unsigned char* lds, const Gemm g, const Sched& S, const Epi& E) {
;     ...
;         const bool has_next = S.next(ui + 1, nxt);
;         const char* nA = has_next ? (const char*)g.A + (size_t)nxt.pm * tstep : cA; const char* nB = has_next ? (const char*)g.Bt + (size_t)nxt.pn * tstep : cB;
;         for (int t = 0; t < nt; t += 2) {
;             const bool last = (t == nt - 2);
;             const char* a1 = cA + (size_t)(t + 1) * kstep;
;             const char* a2 = last ? nA : cA + (size_t)(t + 2) * kstep; const char* b2 = last ? nB : cB + (size_t)(t + 2) * kstep;
;             const char* a3 = a2 + kstep; const char* b3 = b2 + kstep;
;     ...
;             PG8_LDB(B0, 0, 0); PG8_LDB(B1, 0, 1); PG8_SCHED; PG8_LDA(At, 0, 0); PG8_STAGE(PG8_SA(1, 1), a1 + hstep, voffA);
;             PG8_WAIT_V(8); PG8_WAIT_L(0); PG8_BAR; PG8_MMA(0, 0, At, B0); PG8_MMA(0, 1, At, B1); PG8_BAR; PG8_SCHED;
;             PG8_LDA(At, 0, 1); PG8_STAGE(PG8_SB(0, 0), b2, voffB); PG8_STAGE(PG8_SB(0, 1), b2 + hstep, voffB); PG8_STAGE(PG8_SA(0, 0), a2, voffA);
;             PG8_WAIT_V(8); PG8_WAIT_L(0); PG8_BAR; PG8_MMA(1, 0, At, B0); PG8_MMA(1, 1, At, B1); PG8_BAR; PG8_SCHED;
;             PG8_LDB(B0, 1, 0); PG8_LDB(B1, 1, 1); PG8_SCHED; PG8_LDA(At, 1, 0); PG8_STAGE(PG8_SA(0, 1), a2 + hstep, voffA);
;             PG8_WAIT_V(8); PG8_WAIT_L(0); PG8_BAR; PG8_MMA(0, 0, At, B0); PG8_MMA(0, 1, At, B1); PG8_BAR; PG8_SCHED;
;             PG8_LDA(At, 1, 1); PG8_STAGE(PG8_SB(1, 0), b3, voffB); PG8_STAGE(PG8_SB(1, 1), b3 + hstep, voffB); PG8_STAGE(PG8_SA(1, 0), a3, voffA);
;             PG8_WAIT_V(8); PG8_WAIT_L(0); PG8_BAR; PG8_MMA(1, 0, At, B0); PG8_MMA(1, 1, At, B1); PG8_BAR; PG8_SCHED;
	s_setprio 1
	s_waitcnt lgkmcnt(0)
	v_mfma_f32_16x16x32_bf16 v[64:67], v[104:107], v[182:185], v[64:67]
	v_mfma_f32_16x16x32_bf16 v[68:71], v[112:115], v[182:185], v[68:71]
	v_mfma_f32_16x16x32_bf16 v[72:75], v[104:107], v[190:193], v[72:75]
	v_mfma_f32_16x16x32_bf16 v[76:79], v[112:115], v[190:193], v[76:79]
	v_mfma_f32_16x16x32_bf16 v[80:83], v[104:107], v[198:201], v[80:83]
	v_mfma_f32_16x16x32_bf16 v[84:87], v[112:115], v[198:201], v[84:87]
	v_mfma_f32_16x16x32_bf16 v[88:91], v[104:107], v[206:209], v[88:91]
	v_mfma_f32_16x16x32_bf16 v[64:67], v[108:111], v[186:189], v[64:67]
	v_mfma_f32_16x16x32_bf16 v[68:71], v[116:119], v[186:189], v[68:71]
	v_mfma_f32_16x16x32_bf16 v[72:75], v[108:111], v[194:197], v[72:75]
	v_mfma_f32_16x16x32_bf16 v[76:79], v[116:119], v[194:197], v[76:79]
	v_mfma_f32_16x16x32_bf16 v[80:83], v[108:111], v[202:205], v[80:83]
	v_mfma_f32_16x16x32_bf16 v[84:87], v[116:119], v[202:205], v[84:87]
	v_mfma_f32_16x16x32_bf16 v[214:217], v[108:111], v[210:213], v[88:91]
	v_mfma_f32_16x16x32_bf16 v[88:91], v[112:115], v[206:209], v[92:95]
	v_mfma_f32_16x16x32_bf16 v[218:221], v[116:119], v[210:213], v[88:91]
	s_setprio 0
	s_setprio 1
	v_mfma_f32_16x16x32_bf16 v[88:91], v[120:123], v[182:185], v[96:99]
	v_mfma_f32_16x16x32_bf16 v[32:35], v[174:177], v[182:185], v[32:35]
	v_mfma_f32_16x16x32_bf16 v[36:39], v[120:123], v[190:193], v[36:39]
	v_mfma_f32_16x16x32_bf16 v[40:43], v[174:177], v[190:193], v[40:43]
	v_mfma_f32_16x16x32_bf16 v[44:47], v[120:123], v[198:201], v[44:47]
	v_mfma_f32_16x16x32_bf16 v[48:51], v[174:177], v[198:201], v[48:51]
	v_mfma_f32_16x16x32_bf16 v[52:55], v[120:123], v[206:209], v[52:55]
	v_mfma_f32_16x16x32_bf16 v[56:59], v[174:177], v[206:209], v[56:59]
	v_mfma_f32_16x16x32_bf16 v[96:99], v[124:127], v[186:189], v[88:91]
	v_mfma_f32_16x16x32_bf16 v[32:35], v[178:181], v[186:189], v[32:35]
	v_mfma_f32_16x16x32_bf16 v[36:39], v[124:127], v[194:197], v[36:39]
	v_mfma_f32_16x16x32_bf16 v[40:43], v[178:181], v[194:197], v[40:43]
	v_mfma_f32_16x16x32_bf16 v[44:47], v[124:127], v[202:205], v[44:47]
	v_mfma_f32_16x16x32_bf16 v[48:51], v[178:181], v[202:205], v[48:51]
	v_mfma_f32_16x16x32_bf16 v[52:55], v[124:127], v[210:213], v[52:55]
	v_mfma_f32_16x16x32_bf16 v[56:59], v[178:181], v[210:213], v[56:59]
	s_setprio 0
	s_barrier
	s_mov_b32 m0, s75
	v_lshl_add_u64 v[144:145], s[64:65], 0, v[132:133]
	s_add_u32 s52, s64, 0x10000
	ds_read_b128 v[88:91], v151 offset:16384
	ds_read_b128 v[92:95], v151 offset:17408
	ds_read_b128 v[182:185], v151 offset:18432
	ds_read_b128 v[186:189], v151 offset:19456
	ds_read_b128 v[190:193], v151 offset:20480
	ds_read_b128 v[194:197], v151 offset:21504
	ds_read_b128 v[198:201], v151 offset:22528
	ds_read_b128 v[202:205], v151 offset:23552
	global_load_lds_dwordx4 v[144:145], off
	v_lshl_add_u64 v[248:249], s[64:65], 0, v[128:129]
	s_mov_b32 m0, s76
	s_addc_u32 s53, s65, 0
	global_load_lds_dwordx4 v[248:249], off
	v_lshl_add_u64 v[206:207], s[52:53], 0, v[132:133]
	s_mov_b32 m0, s77
	v_lshl_add_u64 v[250:251], s[66:67], 0, v[134:135]
	global_load_lds_dwordx4 v[206:207], off
	v_lshl_add_u64 v[206:207], s[52:53], 0, v[128:129]
	s_mov_b32 m0, s80
	v_lshl_add_u64 v[252:253], s[66:67], 0, v[130:131]
	global_load_lds_dwordx4 v[206:207], off
	s_mov_b32 m0, s43
	s_nop 0
	global_load_lds_dwordx4 v[250:251], off
	s_mov_b32 m0, s61
	s_nop 0
	global_load_lds_dwordx4 v[252:253], off
	s_waitcnt vmcnt(8)
	s_waitcnt lgkmcnt(0)
	s_barrier
	s_setprio 1
	s_waitcnt lgkmcnt(0)
	v_mfma_f32_16x16x32_bf16 v[0:3], v[104:107], v[198:201], v[0:3]
	v_mfma_f32_16x16x32_bf16 v[0:3], v[108:111], v[202:205], v[0:3]
	v_mfma_f32_16x16x32_bf16 v[4:7], v[112:115], v[198:201], v[4:7]
	v_mfma_f32_16x16x32_bf16 v[4:7], v[116:119], v[202:205], v[4:7]
	v_mfma_f32_16x16x32_bf16 v[140:143], v[104:107], v[88:91], v[140:143]
	v_mfma_f32_16x16x32_bf16 v[140:143], v[108:111], v[92:95], v[140:143]
	v_mfma_f32_16x16x32_bf16 v[154:157], v[112:115], v[88:91], v[154:157]
	v_mfma_f32_16x16x32_bf16 v[154:157], v[116:119], v[92:95], v[154:157]
	v_mfma_f32_16x16x32_bf16 v[158:161], v[104:107], v[182:185], v[158:161]
	v_mfma_f32_16x16x32_bf16 v[158:161], v[108:111], v[186:189], v[158:161]
	v_mfma_f32_16x16x32_bf16 v[162:165], v[112:115], v[182:185], v[162:165]
	v_mfma_f32_16x16x32_bf16 v[162:165], v[116:119], v[186:189], v[162:165]
	v_mfma_f32_16x16x32_bf16 v[166:169], v[104:107], v[190:193], v[166:169]
	v_mfma_f32_16x16x32_bf16 v[166:169], v[108:111], v[194:197], v[166:169]
	v_mfma_f32_16x16x32_bf16 v[170:173], v[112:115], v[190:193], v[170:173]
	v_mfma_f32_16x16x32_bf16 v[170:173], v[116:119], v[194:197], v[170:173]
	s_setprio 0
	s_setprio 1
	v_mfma_f32_16x16x32_bf16 v[8:11], v[120:123], v[88:91], v[8:11]
	v_mfma_f32_16x16x32_bf16 v[206:209], v[124:127], v[92:95], v[8:11]
	v_mfma_f32_16x16x32_bf16 v[8:11], v[174:177], v[88:91], v[12:15]
	v_mfma_f32_16x16x32_bf16 v[210:213], v[178:181], v[92:95], v[8:11]
	v_mfma_f32_16x16x32_bf16 v[8:11], v[120:123], v[182:185], v[24:27]
	v_mfma_f32_16x16x32_bf16 v[222:225], v[124:127], v[186:189], v[8:11]
	v_mfma_f32_16x16x32_bf16 v[8:11], v[174:177], v[182:185], v[28:31]
	v_mfma_f32_16x16x32_bf16 v[182:185], v[178:181], v[186:189], v[8:11]
	v_mfma_f32_16x16x32_bf16 v[8:11], v[120:123], v[190:193], v[60:63]
	v_mfma_f32_16x16x32_bf16 v[186:189], v[124:127], v[194:197], v[8:11]
	v_mfma_f32_16x16x32_bf16 v[8:11], v[174:177], v[190:193], v[100:103]
	v_mfma_f32_16x16x32_bf16 v[190:193], v[178:181], v[194:197], v[8:11]
	v_mfma_f32_16x16x32_bf16 v[8:11], v[120:123], v[198:201], v[16:19]
	v_mfma_f32_16x16x32_bf16 v[194:197], v[124:127], v[202:205], v[8:11]
	v_mfma_f32_16x16x32_bf16 v[8:11], v[174:177], v[198:201], v[20:23]
	v_mfma_f32_16x16x32_bf16 v[174:177], v[178:181], v[202:205], v[8:11]
	s_setprio 0
	s_barrier
; #define PG8_STAGE(bufoff, gbase, voff) do { _Pragma("unroll") for (int _i = 0; _i < 2; ++_i) \
;         __builtin_amdgcn_global_load_lds((const unsigned*)((const char*)(gbase) + (voff)[_i]), (PG8_LAS unsigned*)(lds + (bufoff) + ldsw + _i * 8192), 16, 0, 0); } while (0)
; #define PG8_LDA(dst, b, h) do { _Pragma("unroll") for (int m = 0; m < 4; ++m) _Pragma("unroll") for (int k = 0; k < 2; ++k) dst[m][k] = *(const PG8_LAS bf16x8*)(lds + PG8_SA(b, h) + aoff + m * 2048 + k * 1024); } while (0)
; #define PG8_LDB(dst, b, h) do { _Pragma("unroll") for (int n = 0; n < 2; ++n) _Pragma("unroll") for (int k = 0; k < 2; ++k) dst[n][k] = *(const PG8_LAS bf16x8*)(lds + PG8_SB(b, h) + boff + n * 2048 + k * 1024); } while (0)
; #define PG8_MMA(ai, bj, At, Bt) do { __builtin_amdgcn_s_setprio(1); _Pragma("unroll") for (int m = 0; m < 4; ++m) _Pragma("unroll") for (int n = 0; n < 2; ++n) _Pragma("unroll") for (int k = 0; k < 2; ++k) \
;         acc[ai][bj][m][n] = __builtin_amdgcn_mfma_f32_16x16x32_bf16(Bt[n][k], At[m][k], acc[ai][bj][m][n], 0, 0, 0); __builtin_amdgcn_s_setprio(0); } while (0)
; #define PG8_BAR __builtin_amdgcn_s_barrier()
; template <class Epi, class Sched, bool ALIGN_EPI = false, bool SP2 = false>
; __device__ __forceinline__ void gemm_phase(PG8_LAS unsigned char* lds, const Gemm g, const Sched& S, const Epi& E) {
;     ...
;             PG8_LDB(B0, 0, 0); PG8_LDB(B1, 0, 1); PG8_SCHED; PG8_LDA(At, 0, 0); PG8_STAGE(PG8_SA(1, 1), a1 + hstep, voffA);
;             PG8_WAIT_V(8); PG8_WAIT_L(0); PG8_BAR; PG8_MMA(0, 0, At, B0); PG8_MMA(0, 1, At, B1); PG8_BAR; PG8_SCHED;
;             PG8_LDA(At, 0, 1); PG8_STAGE(PG8_SB(0, 0), b2, voffB); PG8_STAGE(PG8_SB(0, 1), b2 + hstep, voffB); PG8_STAGE(PG8_SA(0, 0), a2, voffA);
;             PG8_WAIT_V(8); PG8_WAIT_L(0); PG8_BAR; PG8_MMA(1, 0, At, B0); PG8_MMA(1, 1, At, B1); PG8_BAR; PG8_SCHED;
;             PG8_LDB(B0, 1, 0); PG8_LDB(B1, 1, 1); PG8_SCHED; PG8_LDA(At, 1, 0); PG8_STAGE(PG8_SA(0, 1), a2 + hstep, voffA);
;             PG8_WAIT_V(8); PG8_WAIT_L(0); PG8_BAR; PG8_MMA(0, 0, At, B0); PG8_MMA(0, 1, At, B1); PG8_BAR; PG8_SCHED;
;             PG8_LDA(At, 1, 1); PG8_STAGE(PG8_SB(1, 0), b3, voffB); PG8_STAGE(PG8_SB(1, 1), b3 + hstep, voffB); PG8_STAGE(PG8_SA(1, 0), a3, voffA);
;             PG8_WAIT_V(8); PG8_WAIT_L(0); PG8_BAR; PG8_MMA(1, 0, At, B0); PG8_MMA(1, 1, At, B1); PG8_BAR; PG8_SCHED;
;     ...
;         if (!has_next) break;
	s_nop 4
	ds_read_b128 v[8:11], v152
	ds_read_b128 v[12:15], v152 offset:1024
	ds_read_b128 v[16:19], v152 offset:2048
	ds_read_b128 v[20:23], v152 offset:3072
	ds_read_b128 v[178:181], v153
	ds_read_b128 v[198:201], v153 offset:1024
	ds_read_b128 v[202:205], v153 offset:2048
	ds_read_b128 v[228:231], v153 offset:3072
	s_add_u32 s52, s66, 0x10000
	s_addc_u32 s53, s67, 0
	s_mov_b32 m0, s68
	v_lshl_add_u64 v[88:89], s[52:53], 0, v[134:135]
	ds_read_b128 v[24:27], v151 offset:32768
	ds_read_b128 v[28:31], v151 offset:33792
	ds_read_b128 v[60:63], v151 offset:34816
	ds_read_b128 v[100:103], v151 offset:35840
	ds_read_b128 v[232:235], v151 offset:36864
	ds_read_b128 v[236:239], v151 offset:37888
	ds_read_b128 v[240:243], v151 offset:38912
	ds_read_b128 v[244:247], v151 offset:39936
	global_load_lds_dwordx4 v[88:89], off
	v_lshl_add_u64 v[88:89], s[52:53], 0, v[130:131]
	s_mov_b32 m0, s69
	s_nop 0
	global_load_lds_dwordx4 v[88:89], off
	s_waitcnt vmcnt(8)
	s_waitcnt lgkmcnt(0)
	s_barrier
	s_setprio 1
	s_waitcnt lgkmcnt(0)
	v_mfma_f32_16x16x32_bf16 v[64:67], v[8:11], v[24:27], v[64:67]
	v_mfma_f32_16x16x32_bf16 v[124:127], v[12:15], v[28:31], v[64:67]
	v_mfma_f32_16x16x32_bf16 v[64:67], v[16:19], v[24:27], v[68:71]
	v_mfma_f32_16x16x32_bf16 v[120:123], v[20:23], v[28:31], v[64:67]
	v_mfma_f32_16x16x32_bf16 v[64:67], v[8:11], v[60:63], v[72:75]
	v_mfma_f32_16x16x32_bf16 v[108:111], v[12:15], v[100:103], v[64:67]
	v_mfma_f32_16x16x32_bf16 v[64:67], v[16:19], v[60:63], v[76:79]
	v_mfma_f32_16x16x32_bf16 v[104:107], v[20:23], v[100:103], v[64:67]
	v_mfma_f32_16x16x32_bf16 v[64:67], v[8:11], v[232:235], v[80:83]
	v_mfma_f32_16x16x32_bf16 v[92:95], v[12:15], v[236:239], v[64:67]
	v_mfma_f32_16x16x32_bf16 v[64:67], v[16:19], v[232:235], v[84:87]
	v_mfma_f32_16x16x32_bf16 v[88:91], v[20:23], v[236:239], v[64:67]
	v_mfma_f32_16x16x32_bf16 v[64:67], v[8:11], v[240:243], v[214:217]
	v_mfma_f32_16x16x32_bf16 v[76:79], v[12:15], v[244:247], v[64:67]
	v_mfma_f32_16x16x32_bf16 v[64:67], v[16:19], v[240:243], v[218:221]
	v_mfma_f32_16x16x32_bf16 v[72:75], v[20:23], v[244:247], v[64:67]
	s_setprio 0
	s_setprio 1
	v_mfma_f32_16x16x32_bf16 v[64:67], v[178:181], v[24:27], v[96:99]
	v_mfma_f32_16x16x32_bf16 v[24:27], v[202:205], v[24:27], v[32:35]
	v_mfma_f32_16x16x32_bf16 v[116:119], v[228:231], v[28:31], v[24:27]
	v_mfma_f32_16x16x32_bf16 v[24:27], v[178:181], v[60:63], v[36:39]
	v_mfma_f32_16x16x32_bf16 v[96:99], v[198:201], v[100:103], v[24:27]
	v_mfma_f32_16x16x32_bf16 v[24:27], v[202:205], v[60:63], v[40:43]
	v_mfma_f32_16x16x32_bf16 v[100:103], v[228:231], v[100:103], v[24:27]
	v_mfma_f32_16x16x32_bf16 v[24:27], v[178:181], v[232:235], v[44:47]
	v_mfma_f32_16x16x32_bf16 v[80:83], v[198:201], v[236:239], v[24:27]
	v_mfma_f32_16x16x32_bf16 v[24:27], v[202:205], v[232:235], v[48:51]
	v_mfma_f32_16x16x32_bf16 v[84:87], v[228:231], v[236:239], v[24:27]
	v_mfma_f32_16x16x32_bf16 v[24:27], v[178:181], v[240:243], v[52:55]
	v_mfma_f32_16x16x32_bf16 v[112:115], v[198:201], v[28:31], v[64:67]
	v_mfma_f32_16x16x32_bf16 v[64:67], v[198:201], v[244:247], v[24:27]
	v_mfma_f32_16x16x32_bf16 v[24:27], v[202:205], v[240:243], v[56:59]
	v_mfma_f32_16x16x32_bf16 v[68:71], v[228:231], v[244:247], v[24:27]
	s_setprio 0
	s_barrier
	s_mov_b32 m0, s83
	s_nop 3
	v_lshl_add_u64 v[24:25], v[144:145], 0, s[14:15]
	s_add_u32 s52, s64, 0x10080
	ds_read_b128 v[32:35], v151 offset:49152
	ds_read_b128 v[36:39], v151 offset:50176
	ds_read_b128 v[214:217], v151 offset:51200
	ds_read_b128 v[218:221], v151 offset:52224
	ds_read_b128 v[232:235], v151 offset:53248
	ds_read_b128 v[236:239], v151 offset:54272
	ds_read_b128 v[240:243], v151 offset:55296
	ds_read_b128 v[244:247], v151 offset:56320
	global_load_lds_dwordx4 v[24:25], off
	v_lshl_add_u64 v[24:25], v[248:249], 0, s[14:15]
	s_mov_b32 m0, s35
	s_addc_u32 s53, s65, 0
	global_load_lds_dwordx4 v[24:25], off
	v_lshl_add_u64 v[24:25], s[52:53], 0, v[132:133]
	s_mov_b32 m0, s37
	s_nop 0
	global_load_lds_dwordx4 v[24:25], off
	v_lshl_add_u64 v[24:25], s[52:53], 0, v[128:129]
	s_mov_b32 m0, s62
	s_nop 0
	global_load_lds_dwordx4 v[24:25], off
	v_lshl_add_u64 v[24:25], v[250:251], 0, s[14:15]
	s_mov_b32 m0, s70
	s_nop 0
	global_load_lds_dwordx4 v[24:25], off
	v_lshl_add_u64 v[24:25], v[252:253], 0, s[14:15]
	s_mov_b32 m0, s71
	s_nop 0
	global_load_lds_dwordx4 v[24:25], off
	s_waitcnt vmcnt(8)
	s_waitcnt lgkmcnt(0)
	s_barrier
	s_setprio 1
	s_waitcnt lgkmcnt(0)
	v_mfma_f32_16x16x32_bf16 v[24:27], v[8:11], v[32:35], v[140:143]
	v_mfma_f32_16x16x32_bf16 v[60:63], v[12:15], v[36:39], v[24:27]
	v_mfma_f32_16x16x32_bf16 v[24:27], v[16:19], v[32:35], v[154:157]
	v_mfma_f32_16x16x32_bf16 v[56:59], v[20:23], v[36:39], v[24:27]
	v_mfma_f32_16x16x32_bf16 v[24:27], v[8:11], v[214:217], v[158:161]
	v_mfma_f32_16x16x32_bf16 v[44:47], v[12:15], v[218:221], v[24:27]
	v_mfma_f32_16x16x32_bf16 v[24:27], v[16:19], v[214:217], v[162:165]
	v_mfma_f32_16x16x32_bf16 v[40:43], v[20:23], v[218:221], v[24:27]
	v_mfma_f32_16x16x32_bf16 v[24:27], v[8:11], v[232:235], v[166:169]
	v_mfma_f32_16x16x32_bf16 v[0:3], v[8:11], v[240:243], v[0:3]
	v_mfma_f32_16x16x32_bf16 v[28:31], v[12:15], v[236:239], v[24:27]
	v_mfma_f32_16x16x32_bf16 v[24:27], v[16:19], v[232:235], v[170:173]
	v_mfma_f32_16x16x32_bf16 v[12:15], v[12:15], v[244:247], v[0:3]
	v_mfma_f32_16x16x32_bf16 v[0:3], v[16:19], v[240:243], v[4:7]
	v_mfma_f32_16x16x32_bf16 v[24:27], v[20:23], v[236:239], v[24:27]
	v_mfma_f32_16x16x32_bf16 v[8:11], v[20:23], v[244:247], v[0:3]
	s_setprio 0
	s_setprio 1
	v_mfma_f32_16x16x32_bf16 v[0:3], v[178:181], v[32:35], v[206:209]
	v_mfma_f32_16x16x32_bf16 v[48:51], v[198:201], v[36:39], v[0:3]
	v_mfma_f32_16x16x32_bf16 v[0:3], v[202:205], v[32:35], v[210:213]
	v_mfma_f32_16x16x32_bf16 v[52:55], v[228:231], v[36:39], v[0:3]
	v_mfma_f32_16x16x32_bf16 v[0:3], v[178:181], v[214:217], v[222:225]
	v_mfma_f32_16x16x32_bf16 v[32:35], v[198:201], v[218:221], v[0:3]
	v_mfma_f32_16x16x32_bf16 v[0:3], v[202:205], v[214:217], v[182:185]
	v_mfma_f32_16x16x32_bf16 v[36:39], v[228:231], v[218:221], v[0:3]
	v_mfma_f32_16x16x32_bf16 v[0:3], v[178:181], v[232:235], v[186:189]
	v_mfma_f32_16x16x32_bf16 v[16:19], v[198:201], v[236:239], v[0:3]
	v_mfma_f32_16x16x32_bf16 v[0:3], v[202:205], v[232:235], v[190:193]
	v_mfma_f32_16x16x32_bf16 v[20:23], v[228:231], v[236:239], v[0:3]
	v_mfma_f32_16x16x32_bf16 v[0:3], v[178:181], v[240:243], v[194:197]
	v_mfma_f32_16x16x32_bf16 v[4:7], v[198:201], v[244:247], v[0:3]
	v_mfma_f32_16x16x32_bf16 v[0:3], v[202:205], v[240:243], v[174:177]
	v_mfma_f32_16x16x32_bf16 v[0:3], v[228:231], v[244:247], v[0:3]
	s_setprio 0
	s_barrier
	s_andn2_b64 vcc, exec, s[16:17]
	s_cbranch_vccnz .LBB0_1356
	s_barrier

; #define PG8_STAGE(bufoff, gbase, voff) do { _Pragma("unroll") for (int _i = 0; _i < 2; ++_i) \
;         __builtin_amdgcn_global_load_lds((const unsigned*)((const char*)(gbase) + (voff)[_i]), (PG8_LAS unsigned*)(lds + (bufoff) + ldsw + _i * 8192), 16, 0, 0); } while (0)
; #define PG8_LDA(dst, b, h) do { _Pragma("unroll") for (int m = 0; m < 4; ++m) _Pragma("unroll") for (int k = 0; k < 2; ++k) dst[m][k] = *(const PG8_LAS bf16x8*)(lds + PG8_SA(b, h) + aoff + m * 2048 + k * 1024); } while (0)
; #define PG8_LDB(dst, b, h) do { _Pragma("unroll") for (int n = 0; n < 2; ++n) _Pragma("unroll") for (int k = 0; k < 2; ++k) dst[n][k] = *(const PG8_LAS bf16x8*)(lds + PG8_SB(b, h) + boff + n * 2048 + k * 1024); } while (0)
; #define PG8_MMA(ai, bj, At, Bt) do { __builtin_amdgcn_s_setprio(1); _Pragma("unroll") for (int m = 0; m < 4; ++m) _Pragma("unroll") for (int n = 0; n < 2; ++n) _Pragma("unroll") for (int k = 0; k < 2; ++k) \
;         acc[ai][bj][m][n] = __builtin_amdgcn_mfma_f32_16x16x32_bf16(Bt[n][k], At[m][k], acc[ai][bj][m][n], 0, 0, 0); __builtin_amdgcn_s_setprio(0); } while (0)
; #define PG8_WAIT_V(n) asm volatile("s_waitcnt vmcnt(" #n ")" ::: "memory")
; #define PG8_WAIT_L(n) asm volatile("s_waitcnt lgkmcnt(" #n ")" ::: "memory")
; #define PG8_BAR __builtin_amdgcn_s_barrier()
; #define PG8_SCHED __builtin_amdgcn_sched_barrier(0)
; template <class Epi, class Sched, bool ALIGN_EPI = false, bool SP2 = false>
; __device__ __forceinline__ void gemm_phase(PG8_LAS unsigned char* lds, const Gemm g, const Sched& S, const Epi& E) {
;     ...
;             PG8_LDB(B0, 0, 0); PG8_LDB(B1, 0, 1); PG8_SCHED; PG8_LDA(At, 0, 0); PG8_STAGE(PG8_SA(1, 1), a1 + hstep, voffA);
;             PG8_WAIT_V(8); PG8_WAIT_L(0); PG8_BAR; PG8_MMA(0, 0, At, B0); PG8_MMA(0, 1, At, B1); PG8_BAR; PG8_SCHED;
;             PG8_LDA(At, 0, 1); PG8_STAGE(PG8_SB(0, 0), b2, voffB); PG8_STAGE(PG8_SB(0, 1), b2 + hstep, voffB); PG8_STAGE(PG8_SA(0, 0), a2, voffA);
;             PG8_WAIT_V(8); PG8_WAIT_L(0); PG8_BAR; PG8_MMA(1, 0, At, B0); PG8_MMA(1, 1, At, B1); PG8_BAR; PG8_SCHED;
.Lrj_P4_0:
	s_waitcnt lgkmcnt(0)
	s_barrier
	s_setprio 1
	s_waitcnt lgkmcnt(0)
	v_mfma_f32_16x16x32_bf16 v[140:143], v[56:59], v[186:189], v[140:143]
	v_mfma_f32_16x16x32_bf16 v[140:143], v[60:63], v[190:193], v[140:143]
	v_mfma_f32_16x16x32_bf16 v[136:139], v[72:75], v[186:189], v[136:139]
	v_mfma_f32_16x16x32_bf16 v[136:139], v[76:79], v[190:193], v[136:139]
	v_mfma_f32_16x16x32_bf16 v[124:127], v[56:59], v[194:197], v[124:127]
	v_mfma_f32_16x16x32_bf16 v[124:127], v[60:63], v[198:201], v[124:127]
	v_mfma_f32_16x16x32_bf16 v[120:123], v[72:75], v[194:197], v[120:123]
	v_mfma_f32_16x16x32_bf16 v[120:123], v[76:79], v[198:201], v[120:123]
	v_mfma_f32_16x16x32_bf16 v[108:111], v[56:59], v[202:205], v[108:111]
	v_mfma_f32_16x16x32_bf16 v[108:111], v[60:63], v[206:209], v[108:111]
	v_mfma_f32_16x16x32_bf16 v[104:107], v[72:75], v[202:205], v[104:107]
	v_mfma_f32_16x16x32_bf16 v[104:107], v[76:79], v[206:209], v[104:107]
	v_mfma_f32_16x16x32_bf16 v[92:95], v[56:59], v[210:213], v[92:95]
	v_mfma_f32_16x16x32_bf16 v[92:95], v[60:63], v[214:217], v[92:95]
	v_mfma_f32_16x16x32_bf16 v[88:91], v[72:75], v[210:213], v[88:91]
	v_mfma_f32_16x16x32_bf16 v[88:91], v[76:79], v[214:217], v[88:91]
	s_setprio 0
	s_setprio 1
	v_mfma_f32_16x16x32_bf16 v[132:135], v[162:165], v[186:189], v[132:135]
	v_mfma_f32_16x16x32_bf16 v[132:135], v[166:169], v[190:193], v[132:135]
	v_mfma_f32_16x16x32_bf16 v[128:131], v[178:181], v[186:189], v[128:131]
	v_mfma_f32_16x16x32_bf16 v[128:131], v[182:185], v[190:193], v[128:131]
	v_mfma_f32_16x16x32_bf16 v[116:119], v[162:165], v[194:197], v[116:119]
	v_mfma_f32_16x16x32_bf16 v[116:119], v[166:169], v[198:201], v[116:119]
	v_mfma_f32_16x16x32_bf16 v[112:115], v[178:181], v[194:197], v[112:115]
	v_mfma_f32_16x16x32_bf16 v[112:115], v[182:185], v[198:201], v[112:115]
	v_mfma_f32_16x16x32_bf16 v[100:103], v[162:165], v[202:205], v[100:103]
	v_mfma_f32_16x16x32_bf16 v[100:103], v[166:169], v[206:209], v[100:103]
	v_mfma_f32_16x16x32_bf16 v[96:99], v[178:181], v[202:205], v[96:99]
	v_mfma_f32_16x16x32_bf16 v[96:99], v[182:185], v[206:209], v[96:99]
	v_mfma_f32_16x16x32_bf16 v[84:87], v[162:165], v[210:213], v[84:87]
	v_mfma_f32_16x16x32_bf16 v[84:87], v[166:169], v[214:217], v[84:87]
	v_mfma_f32_16x16x32_bf16 v[80:83], v[178:181], v[210:213], v[80:83]
	v_mfma_f32_16x16x32_bf16 v[80:83], v[182:185], v[214:217], v[80:83]
	s_setprio 0
	s_barrier
	s_add_i32 s76, s64, s41
	v_lshl_add_u64 v[218:219], s[36:37], 0, v[146:147]
	s_mov_b32 m0, s76
	ds_read_b128 v[186:189], v175 offset:16384
	ds_read_b128 v[190:193], v175 offset:17408
	ds_read_b128 v[194:197], v175 offset:18432
	ds_read_b128 v[198:201], v175 offset:19456
	ds_read_b128 v[202:205], v175 offset:20480
	ds_read_b128 v[206:209], v175 offset:21504
	ds_read_b128 v[210:213], v175 offset:22528
	ds_read_b128 v[214:217], v175 offset:23552
	global_load_lds_dwordx4 v[218:219], off
	s_add_i32 m0, s76, 0x2000
	s_add_u32 s76, s36, 0x40000
	v_lshl_add_u64 v[220:221], s[36:37], 0, v[150:151]
	s_addc_u32 s77, s37, 0
	s_add_i32 s80, s65, s41
	global_load_lds_dwordx4 v[220:221], off
	v_lshl_add_u64 v[222:223], s[76:77], 0, v[146:147]
	s_mov_b32 m0, s80
	v_lshl_add_u64 v[224:225], s[38:39], 0, v[148:149]
	global_load_lds_dwordx4 v[222:223], off
	v_lshl_add_u64 v[222:223], s[76:77], 0, v[150:151]
	s_add_i32 m0, s80, 0x2000
	s_nop 0
	global_load_lds_dwordx4 v[222:223], off
	v_lshl_add_u64 v[222:223], s[38:39], 0, v[144:145]
	s_mov_b32 m0, s42
	s_nop 0
	global_load_lds_dwordx4 v[222:223], off
	s_mov_b32 m0, s43
	s_nop 0
	global_load_lds_dwordx4 v[224:225], off
	s_cmp_eq_u32 s99, 1
	s_cbranch_scc1 .Lrw_P4_1
	s_waitcnt vmcnt(8)
	s_branch .Lrj_P4_1

; #define PG8_STAGE(bufoff, gbase, voff) do { _Pragma("unroll") for (int _i = 0; _i < 2; ++_i) \
;         __builtin_amdgcn_global_load_lds((const unsigned*)((const char*)(gbase) + (voff)[_i]), (PG8_LAS unsigned*)(lds + (bufoff) + ldsw + _i * 8192), 16, 0, 0); } while (0)
; #define PG8_LDA(dst, b, h) do { _Pragma("unroll") for (int m = 0; m < 4; ++m) _Pragma("unroll") for (int k = 0; k < 2; ++k) dst[m][k] = *(const PG8_LAS bf16x8*)(lds + PG8_SA(b, h) + aoff + m * 2048 + k * 1024); } while (0)
; #define PG8_LDB(dst, b, h) do { _Pragma("unroll") for (int n = 0; n < 2; ++n) _Pragma("unroll") for (int k = 0; k < 2; ++k) dst[n][k] = *(const PG8_LAS bf16x8*)(lds + PG8_SB(b, h) + boff + n * 2048 + k * 1024); } while (0)
; #define PG8_MMA(ai, bj, At, Bt) do { __builtin_amdgcn_s_setprio(1); _Pragma("unroll") for (int m = 0; m < 4; ++m) _Pragma("unroll") for (int n = 0; n < 2; ++n) _Pragma("unroll") for (int k = 0; k < 2; ++k) \
;         acc[ai][bj][m][n] = __builtin_amdgcn_mfma_f32_16x16x32_bf16(Bt[n][k], At[m][k], acc[ai][bj][m][n], 0, 0, 0); __builtin_amdgcn_s_setprio(0); } while (0)
; #define PG8_WAIT_V(n) asm volatile("s_waitcnt vmcnt(" #n ")" ::: "memory")
; #define PG8_WAIT_L(n) asm volatile("s_waitcnt lgkmcnt(" #n ")" ::: "memory")
; #define PG8_BAR __builtin_amdgcn_s_barrier()
; #define PG8_SCHED __builtin_amdgcn_sched_barrier(0)
; template <class Epi, class Sched, bool ALIGN_EPI = false, bool SP2 = false>
; __device__ __forceinline__ void gemm_phase(PG8_LAS unsigned char* lds, const Gemm g, const Sched& S, const Epi& E) {
;     ...
;             PG8_WAIT_V(8); PG8_WAIT_L(0); PG8_BAR; PG8_MMA(1, 0, At, B0); PG8_MMA(1, 1, At, B1); PG8_BAR; PG8_SCHED;
;             PG8_LDB(B0, 1, 0); PG8_LDB(B1, 1, 1); PG8_SCHED; PG8_LDA(At, 1, 0); PG8_STAGE(PG8_SA(0, 1), a2 + hstep, voffA);
;             PG8_WAIT_V(8); PG8_WAIT_L(0); PG8_BAR; PG8_MMA(0, 0, At, B0); PG8_MMA(0, 1, At, B1); PG8_BAR; PG8_SCHED;
.Lrj_P4_1:
	s_waitcnt lgkmcnt(0)
	s_barrier
	s_setprio 1
	s_waitcnt lgkmcnt(0)
	v_mfma_f32_16x16x32_bf16 v[68:71], v[56:59], v[186:189], v[68:71]
	v_mfma_f32_16x16x32_bf16 v[68:71], v[60:63], v[190:193], v[68:71]
	v_mfma_f32_16x16x32_bf16 v[64:67], v[72:75], v[186:189], v[64:67]
	v_mfma_f32_16x16x32_bf16 v[64:67], v[76:79], v[190:193], v[64:67]
	v_mfma_f32_16x16x32_bf16 v[44:47], v[56:59], v[194:197], v[44:47]
	v_mfma_f32_16x16x32_bf16 v[44:47], v[60:63], v[198:201], v[44:47]
	v_mfma_f32_16x16x32_bf16 v[40:43], v[72:75], v[194:197], v[40:43]
	v_mfma_f32_16x16x32_bf16 v[40:43], v[76:79], v[198:201], v[40:43]
	v_mfma_f32_16x16x32_bf16 v[28:31], v[56:59], v[202:205], v[28:31]
	v_mfma_f32_16x16x32_bf16 v[28:31], v[60:63], v[206:209], v[28:31]
	v_mfma_f32_16x16x32_bf16 v[24:27], v[72:75], v[202:205], v[24:27]
	v_mfma_f32_16x16x32_bf16 v[24:27], v[76:79], v[206:209], v[24:27]
	v_mfma_f32_16x16x32_bf16 v[12:15], v[56:59], v[210:213], v[12:15]
	v_mfma_f32_16x16x32_bf16 v[12:15], v[60:63], v[214:217], v[12:15]
	v_mfma_f32_16x16x32_bf16 v[8:11], v[72:75], v[210:213], v[8:11]
	v_mfma_f32_16x16x32_bf16 v[8:11], v[76:79], v[214:217], v[8:11]
	s_setprio 0
	s_setprio 1
	v_mfma_f32_16x16x32_bf16 v[52:55], v[162:165], v[186:189], v[52:55]
	v_mfma_f32_16x16x32_bf16 v[52:55], v[166:169], v[190:193], v[52:55]
	v_mfma_f32_16x16x32_bf16 v[48:51], v[178:181], v[186:189], v[48:51]
	v_mfma_f32_16x16x32_bf16 v[48:51], v[182:185], v[190:193], v[48:51]
	v_mfma_f32_16x16x32_bf16 v[36:39], v[162:165], v[194:197], v[36:39]
	v_mfma_f32_16x16x32_bf16 v[36:39], v[166:169], v[198:201], v[36:39]
	v_mfma_f32_16x16x32_bf16 v[32:35], v[178:181], v[194:197], v[32:35]
	v_mfma_f32_16x16x32_bf16 v[32:35], v[182:185], v[198:201], v[32:35]
	v_mfma_f32_16x16x32_bf16 v[20:23], v[162:165], v[202:205], v[20:23]
	v_mfma_f32_16x16x32_bf16 v[20:23], v[166:169], v[206:209], v[20:23]
	v_mfma_f32_16x16x32_bf16 v[16:19], v[178:181], v[202:205], v[16:19]
	v_mfma_f32_16x16x32_bf16 v[16:19], v[182:185], v[206:209], v[16:19]
	v_mfma_f32_16x16x32_bf16 v[4:7], v[162:165], v[210:213], v[4:7]
	v_mfma_f32_16x16x32_bf16 v[4:7], v[166:169], v[214:217], v[4:7]
	v_mfma_f32_16x16x32_bf16 v[0:3], v[178:181], v[210:213], v[0:3]
	v_mfma_f32_16x16x32_bf16 v[0:3], v[182:185], v[214:217], v[0:3]
	s_setprio 0
	s_barrier
	s_add_i32 s76, 0, 0x18000
	s_add_i32 s77, 0, 0x1c000
	v_add_u32_e32 v76, s76, v171
	v_add_u32_e32 v152, s77, v171
	ds_read_b128 v[56:59], v76
	ds_read_b128 v[60:63], v76 offset:1024
	ds_read_b128 v[72:75], v76 offset:2048
	ds_read_b128 v[76:79], v76 offset:3072
	ds_read_b128 v[162:165], v152
	ds_read_b128 v[166:169], v152 offset:1024
	ds_read_b128 v[178:181], v152 offset:2048
	ds_read_b128 v[182:185], v152 offset:3072
	s_add_u32 s38, s38, 0x40000
	s_addc_u32 s39, s39, 0
	s_mov_b32 m0, s46
	v_lshl_add_u64 v[228:229], s[38:39], 0, v[144:145]
	ds_read_b128 v[186:189], v175 offset:32768
	ds_read_b128 v[190:193], v175 offset:33792
	ds_read_b128 v[194:197], v175 offset:34816
	ds_read_b128 v[198:201], v175 offset:35840
	ds_read_b128 v[202:205], v175 offset:36864
	ds_read_b128 v[206:209], v175 offset:37888
	ds_read_b128 v[210:213], v175 offset:38912
	ds_read_b128 v[214:217], v175 offset:39936
	global_load_lds_dwordx4 v[228:229], off
	v_lshl_add_u64 v[228:229], s[38:39], 0, v[148:149]
	s_mov_b32 m0, s47
	s_nop 0
	global_load_lds_dwordx4 v[228:229], off
	s_waitcnt vmcnt(8)
	s_waitcnt lgkmcnt(0)
	s_barrier
	s_setprio 1
	s_waitcnt lgkmcnt(0)
	v_mfma_f32_16x16x32_bf16 v[140:143], v[56:59], v[186:189], v[140:143]
	v_mfma_f32_16x16x32_bf16 v[140:143], v[60:63], v[190:193], v[140:143]
	v_mfma_f32_16x16x32_bf16 v[136:139], v[72:75], v[186:189], v[136:139]
	v_mfma_f32_16x16x32_bf16 v[136:139], v[76:79], v[190:193], v[136:139]
	v_mfma_f32_16x16x32_bf16 v[124:127], v[56:59], v[194:197], v[124:127]
	v_mfma_f32_16x16x32_bf16 v[124:127], v[60:63], v[198:201], v[124:127]
	v_mfma_f32_16x16x32_bf16 v[120:123], v[72:75], v[194:197], v[120:123]
	v_mfma_f32_16x16x32_bf16 v[120:123], v[76:79], v[198:201], v[120:123]
	v_mfma_f32_16x16x32_bf16 v[108:111], v[56:59], v[202:205], v[108:111]
	v_mfma_f32_16x16x32_bf16 v[108:111], v[60:63], v[206:209], v[108:111]
	v_mfma_f32_16x16x32_bf16 v[104:107], v[72:75], v[202:205], v[104:107]
	v_mfma_f32_16x16x32_bf16 v[104:107], v[76:79], v[206:209], v[104:107]
	v_mfma_f32_16x16x32_bf16 v[92:95], v[56:59], v[210:213], v[92:95]
	v_mfma_f32_16x16x32_bf16 v[92:95], v[60:63], v[214:217], v[92:95]
	v_mfma_f32_16x16x32_bf16 v[88:91], v[72:75], v[210:213], v[88:91]
	v_mfma_f32_16x16x32_bf16 v[88:91], v[76:79], v[214:217], v[88:91]
	s_setprio 0
	s_setprio 1
	v_mfma_f32_16x16x32_bf16 v[132:135], v[162:165], v[186:189], v[132:135]
	v_mfma_f32_16x16x32_bf16 v[132:135], v[166:169], v[190:193], v[132:135]
	v_mfma_f32_16x16x32_bf16 v[128:131], v[178:181], v[186:189], v[128:131]
	v_mfma_f32_16x16x32_bf16 v[128:131], v[182:185], v[190:193], v[128:131]
	v_mfma_f32_16x16x32_bf16 v[116:119], v[162:165], v[194:197], v[116:119]
	v_mfma_f32_16x16x32_bf16 v[116:119], v[166:169], v[198:201], v[116:119]
	v_mfma_f32_16x16x32_bf16 v[112:115], v[178:181], v[194:197], v[112:115]
	v_mfma_f32_16x16x32_bf16 v[112:115], v[182:185], v[198:201], v[112:115]
	v_mfma_f32_16x16x32_bf16 v[100:103], v[162:165], v[202:205], v[100:103]
	v_mfma_f32_16x16x32_bf16 v[100:103], v[166:169], v[206:209], v[100:103]
	v_mfma_f32_16x16x32_bf16 v[96:99], v[178:181], v[202:205], v[96:99]
	v_mfma_f32_16x16x32_bf16 v[96:99], v[182:185], v[206:209], v[96:99]
	v_mfma_f32_16x16x32_bf16 v[84:87], v[162:165], v[210:213], v[84:87]
	v_mfma_f32_16x16x32_bf16 v[84:87], v[166:169], v[214:217], v[84:87]
	v_mfma_f32_16x16x32_bf16 v[80:83], v[178:181], v[210:213], v[80:83]
	v_mfma_f32_16x16x32_bf16 v[80:83], v[182:185], v[214:217], v[80:83]
	s_setprio 0
	s_barrier
; #define PG8_STAGE(bufoff, gbase, voff) do { _Pragma("unroll") for (int _i = 0; _i < 2; ++_i) \
;         __builtin_amdgcn_global_load_lds((const unsigned*)((const char*)(gbase) + (voff)[_i]), (PG8_LAS unsigned*)(lds + (bufoff) + ldsw + _i * 8192), 16, 0, 0); } while (0)
; #define PG8_LDA(dst, b, h) do { _Pragma("unroll") for (int m = 0; m < 4; ++m) _Pragma("unroll") for (int k = 0; k < 2; ++k) dst[m][k] = *(const PG8_LAS bf16x8*)(lds + PG8_SA(b, h) + aoff + m * 2048 + k * 1024); } while (0)
; #define PG8_MMA(ai, bj, At, Bt) do { __builtin_amdgcn_s_setprio(1); _Pragma("unroll") for (int m = 0; m < 4; ++m) _Pragma("unroll") for (int n = 0; n < 2; ++n) _Pragma("unroll") for (int k = 0; k < 2; ++k) \
;         acc[ai][bj][m][n] = __builtin_amdgcn_mfma_f32_16x16x32_bf16(Bt[n][k], At[m][k], acc[ai][bj][m][n], 0, 0, 0); __builtin_amdgcn_s_setprio(0); } while (0)
; #define PG8_WAIT_V(n) asm volatile("s_waitcnt vmcnt(" #n ")" ::: "memory")
; #define PG8_WAIT_L(n) asm volatile("s_waitcnt lgkmcnt(" #n ")" ::: "memory")
; #define PG8_BAR __builtin_amdgcn_s_barrier()
; #define PG8_SCHED __builtin_amdgcn_sched_barrier(0)
; template <class Epi, class Sched, bool ALIGN_EPI = false, bool SP2 = false>
; __device__ __forceinline__ void gemm_phase(PG8_LAS unsigned char* lds, const Gemm g, const Sched& S, const Epi& E) {
;     ...
;         for (int t = 0; t < nt; t += 2) {
;     ...
;             PG8_LDA(At, 1, 1); PG8_STAGE(PG8_SB(1, 0), b3, voffB); PG8_STAGE(PG8_SB(1, 1), b3 + hstep, voffB); PG8_STAGE(PG8_SA(1, 0), a3, voffA);
;             PG8_WAIT_V(8); PG8_WAIT_L(0); PG8_BAR; PG8_MMA(1, 0, At, B0); PG8_MMA(1, 1, At, B1); PG8_BAR; PG8_SCHED;
	s_add_i32 s38, s76, s41
	v_lshl_add_u64 v[218:219], v[218:219], 0, s[18:19]
	s_mov_b32 m0, s38
	ds_read_b128 v[186:189], v175 offset:49152
	ds_read_b128 v[190:193], v175 offset:50176
	ds_read_b128 v[194:197], v175 offset:51200
	ds_read_b128 v[198:201], v175 offset:52224
	ds_read_b128 v[202:205], v175 offset:53248
	ds_read_b128 v[206:209], v175 offset:54272
	ds_read_b128 v[210:213], v175 offset:55296
	ds_read_b128 v[214:217], v175 offset:56320
	global_load_lds_dwordx4 v[218:219], off
	s_add_i32 m0, s38, 0x2000
	s_add_u32 s36, s36, 0x40080
	v_lshl_add_u64 v[218:219], v[220:221], 0, s[18:19]
	s_addc_u32 s37, s37, 0
	s_add_i32 s38, s77, s41
	global_load_lds_dwordx4 v[218:219], off
	v_lshl_add_u64 v[218:219], s[36:37], 0, v[146:147]
	s_mov_b32 m0, s38
	s_nop 0
	global_load_lds_dwordx4 v[218:219], off
	v_lshl_add_u64 v[218:219], s[36:37], 0, v[150:151]
	s_add_i32 m0, s38, 0x2000
	s_nop 0
	global_load_lds_dwordx4 v[218:219], off
	v_lshl_add_u64 v[218:219], v[222:223], 0, s[18:19]
	s_mov_b32 m0, s53
	s_nop 0
	global_load_lds_dwordx4 v[218:219], off
	v_lshl_add_u64 v[218:219], v[224:225], 0, s[18:19]
	s_mov_b32 m0, s60
	s_nop 0
	global_load_lds_dwordx4 v[218:219], off
	s_waitcnt vmcnt(8)
	s_waitcnt lgkmcnt(0)
	s_barrier
	s_setprio 1
	s_waitcnt lgkmcnt(0)
	v_mfma_f32_16x16x32_bf16 v[68:71], v[56:59], v[186:189], v[68:71]
	v_mfma_f32_16x16x32_bf16 v[68:71], v[60:63], v[190:193], v[68:71]
	v_mfma_f32_16x16x32_bf16 v[64:67], v[72:75], v[186:189], v[64:67]
	v_mfma_f32_16x16x32_bf16 v[64:67], v[76:79], v[190:193], v[64:67]
	v_mfma_f32_16x16x32_bf16 v[44:47], v[56:59], v[194:197], v[44:47]
	v_mfma_f32_16x16x32_bf16 v[44:47], v[60:63], v[198:201], v[44:47]
	v_mfma_f32_16x16x32_bf16 v[40:43], v[72:75], v[194:197], v[40:43]
	v_mfma_f32_16x16x32_bf16 v[40:43], v[76:79], v[198:201], v[40:43]
	v_mfma_f32_16x16x32_bf16 v[28:31], v[56:59], v[202:205], v[28:31]
	v_mfma_f32_16x16x32_bf16 v[28:31], v[60:63], v[206:209], v[28:31]
	v_mfma_f32_16x16x32_bf16 v[24:27], v[72:75], v[202:205], v[24:27]
	v_mfma_f32_16x16x32_bf16 v[24:27], v[76:79], v[206:209], v[24:27]
	v_mfma_f32_16x16x32_bf16 v[12:15], v[56:59], v[210:213], v[12:15]
	v_mfma_f32_16x16x32_bf16 v[12:15], v[60:63], v[214:217], v[12:15]
	v_mfma_f32_16x16x32_bf16 v[8:11], v[72:75], v[210:213], v[8:11]
	v_mfma_f32_16x16x32_bf16 v[8:11], v[76:79], v[214:217], v[8:11]
	s_setprio 0
	s_setprio 1
	v_mfma_f32_16x16x32_bf16 v[52:55], v[162:165], v[186:189], v[52:55]
	v_mfma_f32_16x16x32_bf16 v[52:55], v[166:169], v[190:193], v[52:55]
	v_mfma_f32_16x16x32_bf16 v[48:51], v[178:181], v[186:189], v[48:51]
	v_mfma_f32_16x16x32_bf16 v[48:51], v[182:185], v[190:193], v[48:51]
	v_mfma_f32_16x16x32_bf16 v[36:39], v[162:165], v[194:197], v[36:39]
	v_mfma_f32_16x16x32_bf16 v[36:39], v[166:169], v[198:201], v[36:39]
	v_mfma_f32_16x16x32_bf16 v[32:35], v[178:181], v[194:197], v[32:35]
	v_mfma_f32_16x16x32_bf16 v[32:35], v[182:185], v[198:201], v[32:35]
	v_mfma_f32_16x16x32_bf16 v[20:23], v[162:165], v[202:205], v[20:23]
	v_mfma_f32_16x16x32_bf16 v[20:23], v[166:169], v[206:209], v[20:23]
	v_mfma_f32_16x16x32_bf16 v[16:19], v[178:181], v[202:205], v[16:19]
	v_mfma_f32_16x16x32_bf16 v[16:19], v[182:185], v[206:209], v[16:19]
	v_mfma_f32_16x16x32_bf16 v[4:7], v[162:165], v[210:213], v[4:7]
	v_mfma_f32_16x16x32_bf16 v[4:7], v[166:169], v[214:217], v[4:7]
	v_mfma_f32_16x16x32_bf16 v[0:3], v[178:181], v[210:213], v[0:3]
	v_mfma_f32_16x16x32_bf16 v[0:3], v[182:185], v[214:217], v[0:3]
	s_setprio 0
	s_barrier
	s_mov_b32 s99, 0
	s_add_i32 s75, s75, 2
	s_add_u32 s34, s34, 0x100
	s_addc_u32 s35, s35, 0
	s_add_u32 s73, s73, 0x100
	s_addc_u32 s74, s74, 0
	s_cmp_gt_u32 s75, 13
	s_cbranch_scc0 .LBB0_1423
	s_and_b64 vcc, exec, s[20:21]
	s_cbranch_vccz .LBB0_1426
	s_barrier

; #define PG8_STAGE(bufoff, gbase, voff) do { _Pragma("unroll") for (int _i = 0; _i < 2; ++_i) \
;         __builtin_amdgcn_global_load_lds((const unsigned*)((const char*)(gbase) + (voff)[_i]), (PG8_LAS unsigned*)(lds + (bufoff) + ldsw + _i * 8192), 16, 0, 0); } while (0)
; #define PG8_LDA(dst, b, h) do { _Pragma("unroll") for (int m = 0; m < 4; ++m) _Pragma("unroll") for (int k = 0; k < 2; ++k) dst[m][k] = *(const PG8_LAS bf16x8*)(lds + PG8_SA(b, h) + aoff + m * 2048 + k * 1024); } while (0)
; #define PG8_LDB(dst, b, h) do { _Pragma("unroll") for (int n = 0; n < 2; ++n) _Pragma("unroll") for (int k = 0; k < 2; ++k) dst[n][k] = *(const PG8_LAS bf16x8*)(lds + PG8_SB(b, h) + boff + n * 2048 + k * 1024); } while (0)
; #define PG8_MMA(ai, bj, At, Bt) do { __builtin_amdgcn_s_setprio(1); _Pragma("unroll") for (int m = 0; m < 4; ++m) _Pragma("unroll") for (int n = 0; n < 2; ++n) _Pragma("unroll") for (int k = 0; k < 2; ++k) \
;         acc[ai][bj][m][n] = __builtin_amdgcn_mfma_f32_16x16x32_bf16(Bt[n][k], At[m][k], acc[ai][bj][m][n], 0, 0, 0); __builtin_amdgcn_s_setprio(0); } while (0)
; #define PG8_WAIT_V(n) asm volatile("s_waitcnt vmcnt(" #n ")" ::: "memory")
; #define PG8_WAIT_L(n) asm volatile("s_waitcnt lgkmcnt(" #n ")" ::: "memory")
; #define PG8_BAR __builtin_amdgcn_s_barrier()
; #define PG8_SCHED __builtin_amdgcn_sched_barrier(0)
; template <class Epi, class Sched, bool ALIGN_EPI = false, bool SP2 = false>
; __device__ __forceinline__ void gemm_phase(PG8_LAS unsigned char* lds, const Gemm g, const Sched& S, const Epi& E) {
;     ...
;             PG8_LDB(B0, 0, 0); PG8_LDB(B1, 0, 1); PG8_SCHED; PG8_LDA(At, 0, 0); PG8_STAGE(PG8_SA(1, 1), a1 + hstep, voffA);
;             PG8_WAIT_V(8); PG8_WAIT_L(0); PG8_BAR; PG8_MMA(0, 0, At, B0); PG8_MMA(0, 1, At, B1); PG8_BAR; PG8_SCHED;
;             PG8_LDA(At, 0, 1); PG8_STAGE(PG8_SB(0, 0), b2, voffB); PG8_STAGE(PG8_SB(0, 1), b2 + hstep, voffB); PG8_STAGE(PG8_SA(0, 0), a2, voffA);
;             PG8_WAIT_V(8); PG8_WAIT_L(0); PG8_BAR; PG8_MMA(1, 0, At, B0); PG8_MMA(1, 1, At, B1); PG8_BAR; PG8_SCHED;
.Lrj_P5_0:
	s_waitcnt lgkmcnt(0)
	s_barrier
	s_setprio 1
	s_waitcnt lgkmcnt(0)
	v_mfma_f32_16x16x32_bf16 v[124:127], v[144:147], v[184:187], v[124:127]
	v_mfma_f32_16x16x32_bf16 v[124:127], v[156:159], v[188:191], v[124:127]
	v_mfma_f32_16x16x32_bf16 v[120:123], v[160:163], v[184:187], v[120:123]
	v_mfma_f32_16x16x32_bf16 v[120:123], v[164:167], v[188:191], v[120:123]
	v_mfma_f32_16x16x32_bf16 v[108:111], v[144:147], v[192:195], v[108:111]
	v_mfma_f32_16x16x32_bf16 v[108:111], v[156:159], v[196:199], v[108:111]
	v_mfma_f32_16x16x32_bf16 v[104:107], v[160:163], v[192:195], v[104:107]
	v_mfma_f32_16x16x32_bf16 v[104:107], v[164:167], v[196:199], v[104:107]
	v_mfma_f32_16x16x32_bf16 v[92:95], v[144:147], v[200:203], v[92:95]
	v_mfma_f32_16x16x32_bf16 v[92:95], v[156:159], v[204:207], v[92:95]
	v_mfma_f32_16x16x32_bf16 v[88:91], v[160:163], v[200:203], v[88:91]
	v_mfma_f32_16x16x32_bf16 v[88:91], v[164:167], v[204:207], v[88:91]
	v_mfma_f32_16x16x32_bf16 v[76:79], v[144:147], v[208:211], v[76:79]
	v_mfma_f32_16x16x32_bf16 v[76:79], v[156:159], v[212:215], v[76:79]
	v_mfma_f32_16x16x32_bf16 v[72:75], v[160:163], v[208:211], v[72:75]
	v_mfma_f32_16x16x32_bf16 v[72:75], v[164:167], v[212:215], v[72:75]
	s_setprio 0
	s_setprio 1
	v_mfma_f32_16x16x32_bf16 v[116:119], v[168:171], v[184:187], v[116:119]
	v_mfma_f32_16x16x32_bf16 v[116:119], v[172:175], v[188:191], v[116:119]
	v_mfma_f32_16x16x32_bf16 v[112:115], v[176:179], v[184:187], v[112:115]
	v_mfma_f32_16x16x32_bf16 v[112:115], v[180:183], v[188:191], v[112:115]
	v_mfma_f32_16x16x32_bf16 v[100:103], v[168:171], v[192:195], v[100:103]
	v_mfma_f32_16x16x32_bf16 v[100:103], v[172:175], v[196:199], v[100:103]
	v_mfma_f32_16x16x32_bf16 v[96:99], v[176:179], v[192:195], v[96:99]
	v_mfma_f32_16x16x32_bf16 v[96:99], v[180:183], v[196:199], v[96:99]
	v_mfma_f32_16x16x32_bf16 v[84:87], v[168:171], v[200:203], v[84:87]
	v_mfma_f32_16x16x32_bf16 v[84:87], v[172:175], v[204:207], v[84:87]
	v_mfma_f32_16x16x32_bf16 v[80:83], v[176:179], v[200:203], v[80:83]
	v_mfma_f32_16x16x32_bf16 v[80:83], v[180:183], v[204:207], v[80:83]
	v_mfma_f32_16x16x32_bf16 v[68:71], v[168:171], v[208:211], v[68:71]
	v_mfma_f32_16x16x32_bf16 v[68:71], v[172:175], v[212:215], v[68:71]
	v_mfma_f32_16x16x32_bf16 v[64:67], v[176:179], v[208:211], v[64:67]
	v_mfma_f32_16x16x32_bf16 v[64:67], v[180:183], v[212:215], v[64:67]
	s_setprio 0
	s_barrier
	s_add_i32 s66, s52, s39
	v_lshl_add_u64 v[216:217], s[34:35], 0, v[132:133]
	s_mov_b32 m0, s66
	ds_read_b128 v[184:187], v153 offset:16384
	ds_read_b128 v[188:191], v153 offset:17408
	ds_read_b128 v[192:195], v153 offset:18432
	ds_read_b128 v[196:199], v153 offset:19456
	ds_read_b128 v[200:203], v153 offset:20480
	ds_read_b128 v[204:207], v153 offset:21504
	ds_read_b128 v[208:211], v153 offset:22528
	ds_read_b128 v[212:215], v153 offset:23552
	global_load_lds_dwordx4 v[216:217], off
	s_add_i32 m0, s66, 0x2000
	s_add_u32 s66, s34, 0x40000
	v_lshl_add_u64 v[218:219], s[34:35], 0, v[128:129]
	s_addc_u32 s67, s35, 0
	s_add_i32 s68, s53, s39
	global_load_lds_dwordx4 v[218:219], off
	v_lshl_add_u64 v[220:221], s[66:67], 0, v[132:133]
	s_mov_b32 m0, s68
	v_lshl_add_u64 v[222:223], s[36:37], 0, v[130:131]
	global_load_lds_dwordx4 v[220:221], off
	v_lshl_add_u64 v[220:221], s[66:67], 0, v[128:129]
	s_add_i32 m0, s68, 0x2000
	s_nop 0
	global_load_lds_dwordx4 v[220:221], off
	v_lshl_add_u64 v[220:221], s[36:37], 0, v[134:135]
	s_mov_b32 m0, s29
	s_nop 0
	global_load_lds_dwordx4 v[220:221], off
	s_mov_b32 m0, s42
	s_nop 0
	global_load_lds_dwordx4 v[222:223], off
	s_cmp_eq_u32 s99, 1
	s_cbranch_scc1 .Lrw_P5_1
	s_waitcnt vmcnt(8)
	s_branch .Lrj_P5_1

; #define PG8_STAGE(bufoff, gbase, voff) do { _Pragma("unroll") for (int _i = 0; _i < 2; ++_i) \
;         __builtin_amdgcn_global_load_lds((const unsigned*)((const char*)(gbase) + (voff)[_i]), (PG8_LAS unsigned*)(lds + (bufoff) + ldsw + _i * 8192), 16, 0, 0); } while (0)
; #define PG8_LDA(dst, b, h) do { _Pragma("unroll") for (int m = 0; m < 4; ++m) _Pragma("unroll") for (int k = 0; k < 2; ++k) dst[m][k] = *(const PG8_LAS bf16x8*)(lds + PG8_SA(b, h) + aoff + m * 2048 + k * 1024); } while (0)
; #define PG8_LDB(dst, b, h) do { _Pragma("unroll") for (int n = 0; n < 2; ++n) _Pragma("unroll") for (int k = 0; k < 2; ++k) dst[n][k] = *(const PG8_LAS bf16x8*)(lds + PG8_SB(b, h) + boff + n * 2048 + k * 1024); } while (0)
; #define PG8_MMA(ai, bj, At, Bt) do { __builtin_amdgcn_s_setprio(1); _Pragma("unroll") for (int m = 0; m < 4; ++m) _Pragma("unroll") for (int n = 0; n < 2; ++n) _Pragma("unroll") for (int k = 0; k < 2; ++k) \
;         acc[ai][bj][m][n] = __builtin_amdgcn_mfma_f32_16x16x32_bf16(Bt[n][k], At[m][k], acc[ai][bj][m][n], 0, 0, 0); __builtin_amdgcn_s_setprio(0); } while (0)
; #define PG8_WAIT_V(n) asm volatile("s_waitcnt vmcnt(" #n ")" ::: "memory")
; #define PG8_WAIT_L(n) asm volatile("s_waitcnt lgkmcnt(" #n ")" ::: "memory")
; #define PG8_BAR __builtin_amdgcn_s_barrier()
; #define PG8_SCHED __builtin_amdgcn_sched_barrier(0)
; template <class Epi, class Sched, bool ALIGN_EPI = false, bool SP2 = false>
; __device__ __forceinline__ void gemm_phase(PG8_LAS unsigned char* lds, const Gemm g, const Sched& S, const Epi& E) {
;     ...
;             PG8_WAIT_V(8); PG8_WAIT_L(0); PG8_BAR; PG8_MMA(1, 0, At, B0); PG8_MMA(1, 1, At, B1); PG8_BAR; PG8_SCHED;
;             PG8_LDB(B0, 1, 0); PG8_LDB(B1, 1, 1); PG8_SCHED; PG8_LDA(At, 1, 0); PG8_STAGE(PG8_SA(0, 1), a2 + hstep, voffA);
;             PG8_WAIT_V(8); PG8_WAIT_L(0); PG8_BAR; PG8_MMA(0, 0, At, B0); PG8_MMA(0, 1, At, B1); PG8_BAR; PG8_SCHED;
.Lrj_P5_1:
	s_waitcnt lgkmcnt(0)
	s_barrier
	s_setprio 1
	s_waitcnt lgkmcnt(0)
	v_mfma_f32_16x16x32_bf16 v[60:63], v[144:147], v[184:187], v[60:63]
	v_mfma_f32_16x16x32_bf16 v[60:63], v[156:159], v[188:191], v[60:63]
	v_mfma_f32_16x16x32_bf16 v[56:59], v[160:163], v[184:187], v[56:59]
	v_mfma_f32_16x16x32_bf16 v[56:59], v[164:167], v[188:191], v[56:59]
	v_mfma_f32_16x16x32_bf16 v[44:47], v[144:147], v[192:195], v[44:47]
	v_mfma_f32_16x16x32_bf16 v[44:47], v[156:159], v[196:199], v[44:47]
	v_mfma_f32_16x16x32_bf16 v[40:43], v[160:163], v[192:195], v[40:43]
	v_mfma_f32_16x16x32_bf16 v[40:43], v[164:167], v[196:199], v[40:43]
	v_mfma_f32_16x16x32_bf16 v[28:31], v[144:147], v[200:203], v[28:31]
	v_mfma_f32_16x16x32_bf16 v[28:31], v[156:159], v[204:207], v[28:31]
	v_mfma_f32_16x16x32_bf16 v[24:27], v[160:163], v[200:203], v[24:27]
	v_mfma_f32_16x16x32_bf16 v[24:27], v[164:167], v[204:207], v[24:27]
	v_mfma_f32_16x16x32_bf16 v[12:15], v[144:147], v[208:211], v[12:15]
	v_mfma_f32_16x16x32_bf16 v[12:15], v[156:159], v[212:215], v[12:15]
	v_mfma_f32_16x16x32_bf16 v[8:11], v[160:163], v[208:211], v[8:11]
	v_mfma_f32_16x16x32_bf16 v[8:11], v[164:167], v[212:215], v[8:11]
	s_setprio 0
	s_setprio 1
	v_mfma_f32_16x16x32_bf16 v[52:55], v[168:171], v[184:187], v[52:55]
	v_mfma_f32_16x16x32_bf16 v[52:55], v[172:175], v[188:191], v[52:55]
	v_mfma_f32_16x16x32_bf16 v[48:51], v[176:179], v[184:187], v[48:51]
	v_mfma_f32_16x16x32_bf16 v[48:51], v[180:183], v[188:191], v[48:51]
	v_mfma_f32_16x16x32_bf16 v[36:39], v[168:171], v[192:195], v[36:39]
	v_mfma_f32_16x16x32_bf16 v[36:39], v[172:175], v[196:199], v[36:39]
	v_mfma_f32_16x16x32_bf16 v[32:35], v[176:179], v[192:195], v[32:35]
	v_mfma_f32_16x16x32_bf16 v[32:35], v[180:183], v[196:199], v[32:35]
	v_mfma_f32_16x16x32_bf16 v[20:23], v[168:171], v[200:203], v[20:23]
	v_mfma_f32_16x16x32_bf16 v[20:23], v[172:175], v[204:207], v[20:23]
	v_mfma_f32_16x16x32_bf16 v[16:19], v[176:179], v[200:203], v[16:19]
	v_mfma_f32_16x16x32_bf16 v[16:19], v[180:183], v[204:207], v[16:19]
	v_mfma_f32_16x16x32_bf16 v[4:7], v[168:171], v[208:211], v[4:7]
	v_mfma_f32_16x16x32_bf16 v[4:7], v[172:175], v[212:215], v[4:7]
	v_mfma_f32_16x16x32_bf16 v[0:3], v[176:179], v[208:211], v[0:3]
	v_mfma_f32_16x16x32_bf16 v[0:3], v[180:183], v[212:215], v[0:3]
	s_setprio 0
	s_barrier
	s_add_i32 s66, 0, 0x18000
	v_add_u32_e32 v155, s66, v149
	s_add_i32 s67, 0, 0x1c000
	ds_read_b128 v[144:147], v155
	ds_read_b128 v[156:159], v155 offset:1024
	ds_read_b128 v[160:163], v155 offset:2048
	ds_read_b128 v[164:167], v155 offset:3072
	v_add_u32_e32 v155, s67, v149
	ds_read_b128 v[168:171], v155
	ds_read_b128 v[172:175], v155 offset:1024
	ds_read_b128 v[176:179], v155 offset:2048
	ds_read_b128 v[180:183], v155 offset:3072
	s_add_u32 s36, s36, 0x40000
	s_addc_u32 s37, s37, 0
	s_mov_b32 m0, s43
	v_lshl_add_u64 v[224:225], s[36:37], 0, v[134:135]
	ds_read_b128 v[184:187], v153 offset:32768
	ds_read_b128 v[188:191], v153 offset:33792
	ds_read_b128 v[192:195], v153 offset:34816
	ds_read_b128 v[196:199], v153 offset:35840
	ds_read_b128 v[200:203], v153 offset:36864
	ds_read_b128 v[204:207], v153 offset:37888
	ds_read_b128 v[208:211], v153 offset:38912
	ds_read_b128 v[212:215], v153 offset:39936
	global_load_lds_dwordx4 v[224:225], off
	v_lshl_add_u64 v[224:225], s[36:37], 0, v[130:131]
	s_mov_b32 m0, s46
	s_nop 0
	global_load_lds_dwordx4 v[224:225], off
	s_waitcnt vmcnt(8)
	s_waitcnt lgkmcnt(0)
	s_barrier
	s_setprio 1
	s_waitcnt lgkmcnt(0)
	v_mfma_f32_16x16x32_bf16 v[124:127], v[144:147], v[184:187], v[124:127]
	v_mfma_f32_16x16x32_bf16 v[124:127], v[156:159], v[188:191], v[124:127]
	v_mfma_f32_16x16x32_bf16 v[120:123], v[160:163], v[184:187], v[120:123]
	v_mfma_f32_16x16x32_bf16 v[120:123], v[164:167], v[188:191], v[120:123]
	v_mfma_f32_16x16x32_bf16 v[108:111], v[144:147], v[192:195], v[108:111]
	v_mfma_f32_16x16x32_bf16 v[108:111], v[156:159], v[196:199], v[108:111]
	v_mfma_f32_16x16x32_bf16 v[104:107], v[160:163], v[192:195], v[104:107]
	v_mfma_f32_16x16x32_bf16 v[104:107], v[164:167], v[196:199], v[104:107]
	v_mfma_f32_16x16x32_bf16 v[92:95], v[144:147], v[200:203], v[92:95]
	v_mfma_f32_16x16x32_bf16 v[92:95], v[156:159], v[204:207], v[92:95]
	v_mfma_f32_16x16x32_bf16 v[88:91], v[160:163], v[200:203], v[88:91]
	v_mfma_f32_16x16x32_bf16 v[88:91], v[164:167], v[204:207], v[88:91]
	v_mfma_f32_16x16x32_bf16 v[76:79], v[144:147], v[208:211], v[76:79]
	v_mfma_f32_16x16x32_bf16 v[76:79], v[156:159], v[212:215], v[76:79]
	v_mfma_f32_16x16x32_bf16 v[72:75], v[160:163], v[208:211], v[72:75]
	v_mfma_f32_16x16x32_bf16 v[72:75], v[164:167], v[212:215], v[72:75]
	s_setprio 0
	s_setprio 1
	v_mfma_f32_16x16x32_bf16 v[116:119], v[168:171], v[184:187], v[116:119]
	v_mfma_f32_16x16x32_bf16 v[116:119], v[172:175], v[188:191], v[116:119]
	v_mfma_f32_16x16x32_bf16 v[112:115], v[176:179], v[184:187], v[112:115]
	v_mfma_f32_16x16x32_bf16 v[112:115], v[180:183], v[188:191], v[112:115]
	v_mfma_f32_16x16x32_bf16 v[100:103], v[168:171], v[192:195], v[100:103]
	v_mfma_f32_16x16x32_bf16 v[100:103], v[172:175], v[196:199], v[100:103]
	v_mfma_f32_16x16x32_bf16 v[96:99], v[176:179], v[192:195], v[96:99]
	v_mfma_f32_16x16x32_bf16 v[96:99], v[180:183], v[196:199], v[96:99]
	v_mfma_f32_16x16x32_bf16 v[84:87], v[168:171], v[200:203], v[84:87]
	v_mfma_f32_16x16x32_bf16 v[84:87], v[172:175], v[204:207], v[84:87]
	v_mfma_f32_16x16x32_bf16 v[80:83], v[176:179], v[200:203], v[80:83]
	v_mfma_f32_16x16x32_bf16 v[80:83], v[180:183], v[204:207], v[80:83]
	v_mfma_f32_16x16x32_bf16 v[68:71], v[168:171], v[208:211], v[68:71]
	v_mfma_f32_16x16x32_bf16 v[68:71], v[172:175], v[212:215], v[68:71]
	v_mfma_f32_16x16x32_bf16 v[64:67], v[176:179], v[208:211], v[64:67]
	v_mfma_f32_16x16x32_bf16 v[64:67], v[180:183], v[212:215], v[64:67]
	s_setprio 0
	s_barrier
; #define PG8_STAGE(bufoff, gbase, voff) do { _Pragma("unroll") for (int _i = 0; _i < 2; ++_i) \
;         __builtin_amdgcn_global_load_lds((const unsigned*)((const char*)(gbase) + (voff)[_i]), (PG8_LAS unsigned*)(lds + (bufoff) + ldsw + _i * 8192), 16, 0, 0); } while (0)
; #define PG8_LDA(dst, b, h) do { _Pragma("unroll") for (int m = 0; m < 4; ++m) _Pragma("unroll") for (int k = 0; k < 2; ++k) dst[m][k] = *(const PG8_LAS bf16x8*)(lds + PG8_SA(b, h) + aoff + m * 2048 + k * 1024); } while (0)
; #define PG8_MMA(ai, bj, At, Bt) do { __builtin_amdgcn_s_setprio(1); _Pragma("unroll") for (int m = 0; m < 4; ++m) _Pragma("unroll") for (int n = 0; n < 2; ++n) _Pragma("unroll") for (int k = 0; k < 2; ++k) \
;         acc[ai][bj][m][n] = __builtin_amdgcn_mfma_f32_16x16x32_bf16(Bt[n][k], At[m][k], acc[ai][bj][m][n], 0, 0, 0); __builtin_amdgcn_s_setprio(0); } while (0)
; #define PG8_WAIT_V(n) asm volatile("s_waitcnt vmcnt(" #n ")" ::: "memory")
; #define PG8_WAIT_L(n) asm volatile("s_waitcnt lgkmcnt(" #n ")" ::: "memory")
; #define PG8_BAR __builtin_amdgcn_s_barrier()
; #define PG8_SCHED __builtin_amdgcn_sched_barrier(0)
; template <class Epi, class Sched, bool ALIGN_EPI = false, bool SP2 = false>
; __device__ __forceinline__ void gemm_phase(PG8_LAS unsigned char* lds, const Gemm g, const Sched& S, const Epi& E) {
;     ...
;             PG8_LDA(At, 1, 1); PG8_STAGE(PG8_SB(1, 0), b3, voffB); PG8_STAGE(PG8_SB(1, 1), b3 + hstep, voffB); PG8_STAGE(PG8_SA(1, 0), a3, voffA);
;             PG8_WAIT_V(8); PG8_WAIT_L(0); PG8_BAR; PG8_MMA(1, 0, At, B0); PG8_MMA(1, 1, At, B1); PG8_BAR; PG8_SCHED;
;     __device__ __forceinline__ void operator()(const f32x4 (&acc)[2][2][4][2], const Unit& u, int wr, int wc, int fr, int fq) const {
;     ...
;             for (int m = 0; m < 4; ++m) { const int row = rbase + ai * 128 + m * 16; const f32x4* sp = (const f32x4*)(SSP + (size_t)row * 16);
;                 const f32x4 s4 = (sp[0] + sp[1]) + (sp[2] + sp[3]); const float rstd = __builtin_amdgcn_rsqf(((s4[0] + s4[1]) + (s4[2] + s4[3])) * (1.0f / 1024.0f) + EPS);
	s_add_i32 s36, s66, s39
	v_lshl_add_u64 v[216:217], v[216:217], 0, s[14:15]
	s_mov_b32 m0, s36
	ds_read_b128 v[184:187], v153 offset:49152
	ds_read_b128 v[188:191], v153 offset:50176
	ds_read_b128 v[192:195], v153 offset:51200
	ds_read_b128 v[196:199], v153 offset:52224
	ds_read_b128 v[200:203], v153 offset:53248
	ds_read_b128 v[204:207], v153 offset:54272
	ds_read_b128 v[208:211], v153 offset:55296
	ds_read_b128 v[212:215], v153 offset:56320
	global_load_lds_dwordx4 v[216:217], off
	s_add_i32 m0, s36, 0x2000
	s_add_u32 s34, s34, 0x40080
	v_lshl_add_u64 v[216:217], v[218:219], 0, s[14:15]
	s_addc_u32 s35, s35, 0
	s_add_i32 s36, s67, s39
	global_load_lds_dwordx4 v[216:217], off
	v_lshl_add_u64 v[216:217], s[34:35], 0, v[132:133]
	s_mov_b32 m0, s36
	s_nop 0
	global_load_lds_dwordx4 v[216:217], off
	v_lshl_add_u64 v[216:217], s[34:35], 0, v[128:129]
	s_add_i32 m0, s36, 0x2000
	s_nop 0
	global_load_lds_dwordx4 v[216:217], off
	v_lshl_add_u64 v[216:217], v[220:221], 0, s[14:15]
	s_mov_b32 m0, s49
	s_nop 0
	global_load_lds_dwordx4 v[216:217], off
	v_lshl_add_u64 v[216:217], v[222:223], 0, s[14:15]
	s_mov_b32 m0, s50
	s_nop 0
	global_load_lds_dwordx4 v[216:217], off
	s_waitcnt vmcnt(8)
	s_waitcnt lgkmcnt(0)
	s_barrier
	s_setprio 1
	s_waitcnt lgkmcnt(0)
	v_mfma_f32_16x16x32_bf16 v[60:63], v[144:147], v[184:187], v[60:63]
	v_mfma_f32_16x16x32_bf16 v[60:63], v[156:159], v[188:191], v[60:63]
	v_mfma_f32_16x16x32_bf16 v[56:59], v[160:163], v[184:187], v[56:59]
	v_mfma_f32_16x16x32_bf16 v[56:59], v[164:167], v[188:191], v[56:59]
	v_mfma_f32_16x16x32_bf16 v[44:47], v[144:147], v[192:195], v[44:47]
	v_mfma_f32_16x16x32_bf16 v[44:47], v[156:159], v[196:199], v[44:47]
	v_mfma_f32_16x16x32_bf16 v[40:43], v[160:163], v[192:195], v[40:43]
	v_mfma_f32_16x16x32_bf16 v[40:43], v[164:167], v[196:199], v[40:43]
	v_mfma_f32_16x16x32_bf16 v[28:31], v[144:147], v[200:203], v[28:31]
	v_mfma_f32_16x16x32_bf16 v[28:31], v[156:159], v[204:207], v[28:31]
	v_mfma_f32_16x16x32_bf16 v[24:27], v[160:163], v[200:203], v[24:27]
	v_mfma_f32_16x16x32_bf16 v[24:27], v[164:167], v[204:207], v[24:27]
	v_mfma_f32_16x16x32_bf16 v[12:15], v[144:147], v[208:211], v[12:15]
	v_mfma_f32_16x16x32_bf16 v[12:15], v[156:159], v[212:215], v[12:15]
	v_mfma_f32_16x16x32_bf16 v[8:11], v[160:163], v[208:211], v[8:11]
	v_mfma_f32_16x16x32_bf16 v[8:11], v[164:167], v[212:215], v[8:11]
	s_setprio 0
	s_setprio 1
	v_mfma_f32_16x16x32_bf16 v[52:55], v[168:171], v[184:187], v[52:55]
	v_mfma_f32_16x16x32_bf16 v[52:55], v[172:175], v[188:191], v[52:55]
	v_mfma_f32_16x16x32_bf16 v[48:51], v[176:179], v[184:187], v[48:51]
	v_mfma_f32_16x16x32_bf16 v[48:51], v[180:183], v[188:191], v[48:51]
	v_mfma_f32_16x16x32_bf16 v[36:39], v[168:171], v[192:195], v[36:39]
	v_mfma_f32_16x16x32_bf16 v[36:39], v[172:175], v[196:199], v[36:39]
	v_mfma_f32_16x16x32_bf16 v[32:35], v[176:179], v[192:195], v[32:35]
	v_mfma_f32_16x16x32_bf16 v[32:35], v[180:183], v[196:199], v[32:35]
	v_mfma_f32_16x16x32_bf16 v[20:23], v[168:171], v[200:203], v[20:23]
	v_mfma_f32_16x16x32_bf16 v[20:23], v[172:175], v[204:207], v[20:23]
	v_mfma_f32_16x16x32_bf16 v[16:19], v[176:179], v[200:203], v[16:19]
	v_mfma_f32_16x16x32_bf16 v[16:19], v[180:183], v[204:207], v[16:19]
	v_mfma_f32_16x16x32_bf16 v[4:7], v[168:171], v[208:211], v[4:7]
	v_mfma_f32_16x16x32_bf16 v[4:7], v[172:175], v[212:215], v[4:7]
	v_mfma_f32_16x16x32_bf16 v[0:3], v[176:179], v[208:211], v[0:3]
	v_mfma_f32_16x16x32_bf16 v[0:3], v[180:183], v[212:215], v[0:3]
	s_setprio 0
	s_barrier
	s_mov_b32 s99, 0
	s_add_i32 s65, s65, 2
	s_add_u32 s30, s30, 0x100
	s_addc_u32 s31, s31, 0
	s_add_u32 s63, s63, 0x100
	s_addc_u32 s64, s64, 0
	s_cmp_gt_u32 s65, 13
	s_cbranch_scc0 .LBB0_1540
	v_lshl_add_u32 v146, s28, 8, v148
	v_ashrrev_i32_e32 v147, 31, v146
	v_lshlrev_b64 v[144:145], 6, v[146:147]
	v_lshl_add_u64 v[144:145], s[12:13], 0, v[144:145]
	global_load_dwordx4 v[156:159], v[144:145], off
	global_load_dwordx4 v[160:163], v[144:145], off offset:16
	global_load_dwordx4 v[164:167], v[144:145], off offset:32
	global_load_dwordx4 v[168:171], v[144:145], off offset:48
	global_load_dwordx4 v[172:175], v[144:145], off offset:1024
	global_load_dwordx4 v[176:179], v[144:145], off offset:1040
	global_load_dwordx4 v[180:183], v[144:145], off offset:1056
	global_load_dwordx4 v[184:187], v[144:145], off offset:1072
	global_load_dwordx4 v[188:191], v[144:145], off offset:2048
	global_load_dwordx4 v[192:195], v[144:145], off offset:2064
	global_load_dwordx4 v[196:199], v[144:145], off offset:2080
	global_load_dwordx4 v[200:203], v[144:145], off offset:2096
	global_load_dwordx4 v[204:207], v[144:145], off offset:3072
	global_load_dwordx4 v[208:211], v[144:145], off offset:3088
	global_load_dwordx4 v[212:215], v[144:145], off offset:3104
	global_load_dwordx4 v[216:219], v[144:145], off offset:3120
	s_and_b64 vcc, exec, s[16:17]
	s_cbranch_vccz .LBB0_1543
	s_barrier

; #define PG8_STAGE(bufoff, gbase, voff) do { _Pragma("unroll") for (int _i = 0; _i < 2; ++_i) \
;         __builtin_amdgcn_global_load_lds((const unsigned*)((const char*)(gbase) + (voff)[_i]), (PG8_LAS unsigned*)(lds + (bufoff) + ldsw + _i * 8192), 16, 0, 0); } while (0)
; #define PG8_LDA(dst, b, h) do { _Pragma("unroll") for (int m = 0; m < 4; ++m) _Pragma("unroll") for (int k = 0; k < 2; ++k) dst[m][k] = *(const PG8_LAS bf16x8*)(lds + PG8_SA(b, h) + aoff + m * 2048 + k * 1024); } while (0)
; #define PG8_LDB(dst, b, h) do { _Pragma("unroll") for (int n = 0; n < 2; ++n) _Pragma("unroll") for (int k = 0; k < 2; ++k) dst[n][k] = *(const PG8_LAS bf16x8*)(lds + PG8_SB(b, h) + boff + n * 2048 + k * 1024); } while (0)
; #define PG8_MMA(ai, bj, At, Bt) do { __builtin_amdgcn_s_setprio(1); _Pragma("unroll") for (int m = 0; m < 4; ++m) _Pragma("unroll") for (int n = 0; n < 2; ++n) _Pragma("unroll") for (int k = 0; k < 2; ++k) \
;         acc[ai][bj][m][n] = __builtin_amdgcn_mfma_f32_16x16x32_bf16(Bt[n][k], At[m][k], acc[ai][bj][m][n], 0, 0, 0); __builtin_amdgcn_s_setprio(0); } while (0)
; #define PG8_WAIT_V(n) asm volatile("s_waitcnt vmcnt(" #n ")" ::: "memory")
; #define PG8_WAIT_L(n) asm volatile("s_waitcnt lgkmcnt(" #n ")" ::: "memory")
; #define PG8_BAR __builtin_amdgcn_s_barrier()
; #define PG8_SCHED __builtin_amdgcn_sched_barrier(0)
; template <class Epi, class Sched, bool ALIGN_EPI = false, bool SP2 = false>
; __device__ __forceinline__ void gemm_phase(PG8_LAS unsigned char* lds, const Gemm g, const Sched& S, const Epi& E) {
;     ...
;             PG8_LDB(B0, 0, 0); PG8_LDB(B1, 0, 1); PG8_SCHED; PG8_LDA(At, 0, 0); PG8_STAGE(PG8_SA(1, 1), a1 + hstep, voffA);
;             PG8_WAIT_V(8); PG8_WAIT_L(0); PG8_BAR; PG8_MMA(0, 0, At, B0); PG8_MMA(0, 1, At, B1); PG8_BAR; PG8_SCHED;
;             PG8_LDA(At, 0, 1); PG8_STAGE(PG8_SB(0, 0), b2, voffB); PG8_STAGE(PG8_SB(0, 1), b2 + hstep, voffB); PG8_STAGE(PG8_SA(0, 0), a2, voffA);
;             PG8_WAIT_V(8); PG8_WAIT_L(0); PG8_BAR; PG8_MMA(1, 0, At, B0); PG8_MMA(1, 1, At, B1); PG8_BAR; PG8_SCHED;
.Lrj_P6_0:
	s_waitcnt lgkmcnt(0)
	s_barrier
	s_setprio 1
	s_waitcnt lgkmcnt(0)
	v_mfma_f32_16x16x32_bf16 v[124:127], v[152:155], v[184:187], v[124:127]
	v_mfma_f32_16x16x32_bf16 v[124:127], v[156:159], v[188:191], v[124:127]
	v_mfma_f32_16x16x32_bf16 v[120:123], v[160:163], v[184:187], v[120:123]
	v_mfma_f32_16x16x32_bf16 v[120:123], v[164:167], v[188:191], v[120:123]
	v_mfma_f32_16x16x32_bf16 v[108:111], v[152:155], v[192:195], v[108:111]
	v_mfma_f32_16x16x32_bf16 v[108:111], v[156:159], v[196:199], v[108:111]
	v_mfma_f32_16x16x32_bf16 v[104:107], v[160:163], v[192:195], v[104:107]
	v_mfma_f32_16x16x32_bf16 v[104:107], v[164:167], v[196:199], v[104:107]
	v_mfma_f32_16x16x32_bf16 v[92:95], v[152:155], v[200:203], v[92:95]
	v_mfma_f32_16x16x32_bf16 v[92:95], v[156:159], v[204:207], v[92:95]
	v_mfma_f32_16x16x32_bf16 v[88:91], v[160:163], v[200:203], v[88:91]
	v_mfma_f32_16x16x32_bf16 v[88:91], v[164:167], v[204:207], v[88:91]
	v_mfma_f32_16x16x32_bf16 v[76:79], v[152:155], v[208:211], v[76:79]
	v_mfma_f32_16x16x32_bf16 v[76:79], v[156:159], v[212:215], v[76:79]
	v_mfma_f32_16x16x32_bf16 v[72:75], v[160:163], v[208:211], v[72:75]
	v_mfma_f32_16x16x32_bf16 v[72:75], v[164:167], v[212:215], v[72:75]
	s_setprio 0
	s_setprio 1
	v_mfma_f32_16x16x32_bf16 v[116:119], v[168:171], v[184:187], v[116:119]
	v_mfma_f32_16x16x32_bf16 v[116:119], v[172:175], v[188:191], v[116:119]
	v_mfma_f32_16x16x32_bf16 v[112:115], v[176:179], v[184:187], v[112:115]
	v_mfma_f32_16x16x32_bf16 v[112:115], v[180:183], v[188:191], v[112:115]
	v_mfma_f32_16x16x32_bf16 v[100:103], v[168:171], v[192:195], v[100:103]
	v_mfma_f32_16x16x32_bf16 v[100:103], v[172:175], v[196:199], v[100:103]
	v_mfma_f32_16x16x32_bf16 v[96:99], v[176:179], v[192:195], v[96:99]
	v_mfma_f32_16x16x32_bf16 v[96:99], v[180:183], v[196:199], v[96:99]
	v_mfma_f32_16x16x32_bf16 v[84:87], v[168:171], v[200:203], v[84:87]
	v_mfma_f32_16x16x32_bf16 v[84:87], v[172:175], v[204:207], v[84:87]
	v_mfma_f32_16x16x32_bf16 v[80:83], v[176:179], v[200:203], v[80:83]
	v_mfma_f32_16x16x32_bf16 v[80:83], v[180:183], v[204:207], v[80:83]
	v_mfma_f32_16x16x32_bf16 v[68:71], v[168:171], v[208:211], v[68:71]
	v_mfma_f32_16x16x32_bf16 v[68:71], v[172:175], v[212:215], v[68:71]
	v_mfma_f32_16x16x32_bf16 v[64:67], v[176:179], v[208:211], v[64:67]
	v_mfma_f32_16x16x32_bf16 v[64:67], v[180:183], v[212:215], v[64:67]
	s_setprio 0
	s_barrier
	s_add_i32 s69, s51, s39
	v_lshl_add_u64 v[144:145], s[30:31], 0, v[132:133]
	s_mov_b32 m0, s69
	ds_read_b128 v[184:187], v151 offset:16384
	ds_read_b128 v[188:191], v151 offset:17408
	ds_read_b128 v[192:195], v151 offset:18432
	ds_read_b128 v[196:199], v151 offset:19456
	ds_read_b128 v[200:203], v151 offset:20480
	ds_read_b128 v[204:207], v151 offset:21504
	ds_read_b128 v[208:211], v151 offset:22528
	ds_read_b128 v[212:215], v151 offset:23552
	global_load_lds_dwordx4 v[144:145], off
	s_add_i32 m0, s69, 0x2000
	s_add_u32 s70, s30, 0x100000
	v_lshl_add_u64 v[216:217], s[30:31], 0, v[128:129]
	s_addc_u32 s71, s31, 0
	s_add_i32 s69, s52, s39
	global_load_lds_dwordx4 v[216:217], off
	v_lshl_add_u64 v[218:219], s[70:71], 0, v[132:133]
	s_mov_b32 m0, s69
	v_lshl_add_u64 v[220:221], s[34:35], 0, v[130:131]
	global_load_lds_dwordx4 v[218:219], off
	v_lshl_add_u64 v[218:219], s[70:71], 0, v[128:129]
	s_add_i32 m0, s69, 0x2000
	s_nop 0
	global_load_lds_dwordx4 v[218:219], off
	v_lshl_add_u64 v[218:219], s[34:35], 0, v[134:135]
	s_mov_b32 m0, s27
	s_nop 0
	global_load_lds_dwordx4 v[218:219], off
	s_mov_b32 m0, s42
	s_nop 0
	global_load_lds_dwordx4 v[220:221], off
	s_cmp_eq_u32 s99, 1
	s_cbranch_scc1 .Lrw_P6_1
	s_waitcnt vmcnt(8)
	s_branch .Lrj_P6_1

; #define PG8_STAGE(bufoff, gbase, voff) do { _Pragma("unroll") for (int _i = 0; _i < 2; ++_i) \
;         __builtin_amdgcn_global_load_lds((const unsigned*)((const char*)(gbase) + (voff)[_i]), (PG8_LAS unsigned*)(lds + (bufoff) + ldsw + _i * 8192), 16, 0, 0); } while (0)
; #define PG8_LDA(dst, b, h) do { _Pragma("unroll") for (int m = 0; m < 4; ++m) _Pragma("unroll") for (int k = 0; k < 2; ++k) dst[m][k] = *(const PG8_LAS bf16x8*)(lds + PG8_SA(b, h) + aoff + m * 2048 + k * 1024); } while (0)
; #define PG8_LDB(dst, b, h) do { _Pragma("unroll") for (int n = 0; n < 2; ++n) _Pragma("unroll") for (int k = 0; k < 2; ++k) dst[n][k] = *(const PG8_LAS bf16x8*)(lds + PG8_SB(b, h) + boff + n * 2048 + k * 1024); } while (0)
; #define PG8_MMA(ai, bj, At, Bt) do { __builtin_amdgcn_s_setprio(1); _Pragma("unroll") for (int m = 0; m < 4; ++m) _Pragma("unroll") for (int n = 0; n < 2; ++n) _Pragma("unroll") for (int k = 0; k < 2; ++k) \
;         acc[ai][bj][m][n] = __builtin_amdgcn_mfma_f32_16x16x32_bf16(Bt[n][k], At[m][k], acc[ai][bj][m][n], 0, 0, 0); __builtin_amdgcn_s_setprio(0); } while (0)
; #define PG8_WAIT_V(n) asm volatile("s_waitcnt vmcnt(" #n ")" ::: "memory")
; #define PG8_WAIT_L(n) asm volatile("s_waitcnt lgkmcnt(" #n ")" ::: "memory")
; #define PG8_BAR __builtin_amdgcn_s_barrier()
; #define PG8_SCHED __builtin_amdgcn_sched_barrier(0)
; template <class Epi, class Sched, bool ALIGN_EPI = false, bool SP2 = false>
; __device__ __forceinline__ void gemm_phase(PG8_LAS unsigned char* lds, const Gemm g, const Sched& S, const Epi& E) {
;     ...
;             PG8_WAIT_V(8); PG8_WAIT_L(0); PG8_BAR; PG8_MMA(1, 0, At, B0); PG8_MMA(1, 1, At, B1); PG8_BAR; PG8_SCHED;
;             PG8_LDB(B0, 1, 0); PG8_LDB(B1, 1, 1); PG8_SCHED; PG8_LDA(At, 1, 0); PG8_STAGE(PG8_SA(0, 1), a2 + hstep, voffA);
;             PG8_WAIT_V(8); PG8_WAIT_L(0); PG8_BAR; PG8_MMA(0, 0, At, B0); PG8_MMA(0, 1, At, B1); PG8_BAR; PG8_SCHED;
.Lrj_P6_1:
	s_waitcnt lgkmcnt(0)
	s_barrier
	s_setprio 1
	s_waitcnt lgkmcnt(0)
	v_mfma_f32_16x16x32_bf16 v[60:63], v[152:155], v[184:187], v[60:63]
	v_mfma_f32_16x16x32_bf16 v[60:63], v[156:159], v[188:191], v[60:63]
	v_mfma_f32_16x16x32_bf16 v[56:59], v[160:163], v[184:187], v[56:59]
	v_mfma_f32_16x16x32_bf16 v[56:59], v[164:167], v[188:191], v[56:59]
	v_mfma_f32_16x16x32_bf16 v[44:47], v[152:155], v[192:195], v[44:47]
	v_mfma_f32_16x16x32_bf16 v[44:47], v[156:159], v[196:199], v[44:47]
	v_mfma_f32_16x16x32_bf16 v[40:43], v[160:163], v[192:195], v[40:43]
	v_mfma_f32_16x16x32_bf16 v[40:43], v[164:167], v[196:199], v[40:43]
	v_mfma_f32_16x16x32_bf16 v[28:31], v[152:155], v[200:203], v[28:31]
	v_mfma_f32_16x16x32_bf16 v[28:31], v[156:159], v[204:207], v[28:31]
	v_mfma_f32_16x16x32_bf16 v[24:27], v[160:163], v[200:203], v[24:27]
	v_mfma_f32_16x16x32_bf16 v[24:27], v[164:167], v[204:207], v[24:27]
	v_mfma_f32_16x16x32_bf16 v[12:15], v[152:155], v[208:211], v[12:15]
	v_mfma_f32_16x16x32_bf16 v[12:15], v[156:159], v[212:215], v[12:15]
	v_mfma_f32_16x16x32_bf16 v[8:11], v[160:163], v[208:211], v[8:11]
	v_mfma_f32_16x16x32_bf16 v[8:11], v[164:167], v[212:215], v[8:11]
	s_setprio 0
	s_setprio 1
	v_mfma_f32_16x16x32_bf16 v[52:55], v[168:171], v[184:187], v[52:55]
	v_mfma_f32_16x16x32_bf16 v[52:55], v[172:175], v[188:191], v[52:55]
	v_mfma_f32_16x16x32_bf16 v[48:51], v[176:179], v[184:187], v[48:51]
	v_mfma_f32_16x16x32_bf16 v[48:51], v[180:183], v[188:191], v[48:51]
	v_mfma_f32_16x16x32_bf16 v[36:39], v[168:171], v[192:195], v[36:39]
	v_mfma_f32_16x16x32_bf16 v[36:39], v[172:175], v[196:199], v[36:39]
	v_mfma_f32_16x16x32_bf16 v[32:35], v[176:179], v[192:195], v[32:35]
	v_mfma_f32_16x16x32_bf16 v[32:35], v[180:183], v[196:199], v[32:35]
	v_mfma_f32_16x16x32_bf16 v[20:23], v[168:171], v[200:203], v[20:23]
	v_mfma_f32_16x16x32_bf16 v[20:23], v[172:175], v[204:207], v[20:23]
	v_mfma_f32_16x16x32_bf16 v[16:19], v[176:179], v[200:203], v[16:19]
	v_mfma_f32_16x16x32_bf16 v[16:19], v[180:183], v[204:207], v[16:19]
	v_mfma_f32_16x16x32_bf16 v[4:7], v[168:171], v[208:211], v[4:7]
	v_mfma_f32_16x16x32_bf16 v[4:7], v[172:175], v[212:215], v[4:7]
	v_mfma_f32_16x16x32_bf16 v[0:3], v[176:179], v[208:211], v[0:3]
	v_mfma_f32_16x16x32_bf16 v[0:3], v[180:183], v[212:215], v[0:3]
	s_setprio 0
	s_barrier
	s_add_i32 s69, 0, 0x18000
	s_add_i32 s70, 0, 0x1c000
	v_add_u32_e32 v164, s69, v147
	v_add_u32_e32 v180, s70, v147
	ds_read_b128 v[152:155], v164
	ds_read_b128 v[156:159], v164 offset:1024
	ds_read_b128 v[160:163], v164 offset:2048
	ds_read_b128 v[164:167], v164 offset:3072
	ds_read_b128 v[168:171], v180
	ds_read_b128 v[172:175], v180 offset:1024
	ds_read_b128 v[176:179], v180 offset:2048
	ds_read_b128 v[180:183], v180 offset:3072
	s_add_u32 s34, s34, 0x100000
	s_addc_u32 s35, s35, 0
	s_mov_b32 m0, s43
	v_lshl_add_u64 v[222:223], s[34:35], 0, v[134:135]
	ds_read_b128 v[184:187], v151 offset:32768
	ds_read_b128 v[188:191], v151 offset:33792
	ds_read_b128 v[192:195], v151 offset:34816
	ds_read_b128 v[196:199], v151 offset:35840
	ds_read_b128 v[200:203], v151 offset:36864
	ds_read_b128 v[204:207], v151 offset:37888
	ds_read_b128 v[208:211], v151 offset:38912
	ds_read_b128 v[212:215], v151 offset:39936
	global_load_lds_dwordx4 v[222:223], off
	v_lshl_add_u64 v[222:223], s[34:35], 0, v[130:131]
	s_mov_b32 m0, s46
	s_nop 0
	global_load_lds_dwordx4 v[222:223], off
	s_waitcnt vmcnt(8)
	s_waitcnt lgkmcnt(0)
	s_barrier
	s_setprio 1
	s_waitcnt lgkmcnt(0)
	v_mfma_f32_16x16x32_bf16 v[124:127], v[152:155], v[184:187], v[124:127]
	v_mfma_f32_16x16x32_bf16 v[124:127], v[156:159], v[188:191], v[124:127]
	v_mfma_f32_16x16x32_bf16 v[120:123], v[160:163], v[184:187], v[120:123]
	v_mfma_f32_16x16x32_bf16 v[120:123], v[164:167], v[188:191], v[120:123]
	v_mfma_f32_16x16x32_bf16 v[108:111], v[152:155], v[192:195], v[108:111]
	v_mfma_f32_16x16x32_bf16 v[108:111], v[156:159], v[196:199], v[108:111]
	v_mfma_f32_16x16x32_bf16 v[104:107], v[160:163], v[192:195], v[104:107]
	v_mfma_f32_16x16x32_bf16 v[104:107], v[164:167], v[196:199], v[104:107]
	v_mfma_f32_16x16x32_bf16 v[92:95], v[152:155], v[200:203], v[92:95]
	v_mfma_f32_16x16x32_bf16 v[92:95], v[156:159], v[204:207], v[92:95]
	v_mfma_f32_16x16x32_bf16 v[88:91], v[160:163], v[200:203], v[88:91]
	v_mfma_f32_16x16x32_bf16 v[88:91], v[164:167], v[204:207], v[88:91]
	v_mfma_f32_16x16x32_bf16 v[76:79], v[152:155], v[208:211], v[76:79]
	v_mfma_f32_16x16x32_bf16 v[76:79], v[156:159], v[212:215], v[76:79]
	v_mfma_f32_16x16x32_bf16 v[72:75], v[160:163], v[208:211], v[72:75]
	v_mfma_f32_16x16x32_bf16 v[72:75], v[164:167], v[212:215], v[72:75]
	s_setprio 0
	s_setprio 1
	v_mfma_f32_16x16x32_bf16 v[116:119], v[168:171], v[184:187], v[116:119]
	v_mfma_f32_16x16x32_bf16 v[116:119], v[172:175], v[188:191], v[116:119]
	v_mfma_f32_16x16x32_bf16 v[112:115], v[176:179], v[184:187], v[112:115]
	v_mfma_f32_16x16x32_bf16 v[112:115], v[180:183], v[188:191], v[112:115]
	v_mfma_f32_16x16x32_bf16 v[100:103], v[168:171], v[192:195], v[100:103]
	v_mfma_f32_16x16x32_bf16 v[100:103], v[172:175], v[196:199], v[100:103]
	v_mfma_f32_16x16x32_bf16 v[96:99], v[176:179], v[192:195], v[96:99]
	v_mfma_f32_16x16x32_bf16 v[96:99], v[180:183], v[196:199], v[96:99]
	v_mfma_f32_16x16x32_bf16 v[84:87], v[168:171], v[200:203], v[84:87]
	v_mfma_f32_16x16x32_bf16 v[84:87], v[172:175], v[204:207], v[84:87]
	v_mfma_f32_16x16x32_bf16 v[80:83], v[176:179], v[200:203], v[80:83]
	v_mfma_f32_16x16x32_bf16 v[80:83], v[180:183], v[204:207], v[80:83]
	v_mfma_f32_16x16x32_bf16 v[68:71], v[168:171], v[208:211], v[68:71]
	v_mfma_f32_16x16x32_bf16 v[68:71], v[172:175], v[212:215], v[68:71]
	v_mfma_f32_16x16x32_bf16 v[64:67], v[176:179], v[208:211], v[64:67]
	v_mfma_f32_16x16x32_bf16 v[64:67], v[180:183], v[212:215], v[64:67]
	s_setprio 0
	s_barrier
; #define PG8_STAGE(bufoff, gbase, voff) do { _Pragma("unroll") for (int _i = 0; _i < 2; ++_i) \
;         __builtin_amdgcn_global_load_lds((const unsigned*)((const char*)(gbase) + (voff)[_i]), (PG8_LAS unsigned*)(lds + (bufoff) + ldsw + _i * 8192), 16, 0, 0); } while (0)
; #define PG8_LDA(dst, b, h) do { _Pragma("unroll") for (int m = 0; m < 4; ++m) _Pragma("unroll") for (int k = 0; k < 2; ++k) dst[m][k] = *(const PG8_LAS bf16x8*)(lds + PG8_SA(b, h) + aoff + m * 2048 + k * 1024); } while (0)
; #define PG8_MMA(ai, bj, At, Bt) do { __builtin_amdgcn_s_setprio(1); _Pragma("unroll") for (int m = 0; m < 4; ++m) _Pragma("unroll") for (int n = 0; n < 2; ++n) _Pragma("unroll") for (int k = 0; k < 2; ++k) \
;         acc[ai][bj][m][n] = __builtin_amdgcn_mfma_f32_16x16x32_bf16(Bt[n][k], At[m][k], acc[ai][bj][m][n], 0, 0, 0); __builtin_amdgcn_s_setprio(0); } while (0)
; #define PG8_WAIT_V(n) asm volatile("s_waitcnt vmcnt(" #n ")" ::: "memory")
; #define PG8_WAIT_L(n) asm volatile("s_waitcnt lgkmcnt(" #n ")" ::: "memory")
; #define PG8_BAR __builtin_amdgcn_s_barrier()
; #define PG8_SCHED __builtin_amdgcn_sched_barrier(0)
; template <class Epi, class Sched, bool ALIGN_EPI = false, bool SP2 = false>
; __device__ __forceinline__ void gemm_phase(PG8_LAS unsigned char* lds, const Gemm g, const Sched& S, const Epi& E) {
;     ...
;             PG8_LDA(At, 1, 1); PG8_STAGE(PG8_SB(1, 0), b3, voffB); PG8_STAGE(PG8_SB(1, 1), b3 + hstep, voffB); PG8_STAGE(PG8_SA(1, 0), a3, voffA);
;             PG8_WAIT_V(8); PG8_WAIT_L(0); PG8_BAR; PG8_MMA(1, 0, At, B0); PG8_MMA(1, 1, At, B1); PG8_BAR; PG8_SCHED;
;     __device__ __forceinline__ void operator()(const f32x4 (&acc)[2][2][4][2], const Unit& u, int wr, int wc, int fr, int fq) const {
;     ...
;             for (int m = 0; m < 4; ++m) { float* yr = y + (size_t)(rbase + ai * 128 + m * 16) * 1024 + cb;
; #pragma unroll
;                 for (int bj = 0; bj < 2; ++bj) { float* yp = yr + bj * 128; const f32x4 a = *(const f32x4*)yp + acc[ai][bj][m][0], b = *(const f32x4*)(yp + 4) + acc[ai][bj][m][1]; *(f32x4*)yp = a; *(f32x4*)(yp + 4) = b; }
	s_add_i32 s34, s69, s39
	v_lshl_add_u64 v[144:145], v[144:145], 0, s[6:7]
	s_mov_b32 m0, s34
	ds_read_b128 v[184:187], v151 offset:49152
	ds_read_b128 v[188:191], v151 offset:50176
	ds_read_b128 v[192:195], v151 offset:51200
	ds_read_b128 v[196:199], v151 offset:52224
	ds_read_b128 v[200:203], v151 offset:53248
	ds_read_b128 v[204:207], v151 offset:54272
	ds_read_b128 v[208:211], v151 offset:55296
	ds_read_b128 v[212:215], v151 offset:56320
	global_load_lds_dwordx4 v[144:145], off
	s_add_i32 m0, s34, 0x2000
	s_add_u32 s30, s30, 0x100080
	v_lshl_add_u64 v[144:145], v[216:217], 0, s[6:7]
	s_addc_u32 s31, s31, 0
	s_add_i32 s34, s70, s39
	global_load_lds_dwordx4 v[144:145], off
	v_lshl_add_u64 v[144:145], s[30:31], 0, v[132:133]
	s_mov_b32 m0, s34
	s_nop 0
	global_load_lds_dwordx4 v[144:145], off
	v_lshl_add_u64 v[144:145], s[30:31], 0, v[128:129]
	s_add_i32 m0, s34, 0x2000
	s_nop 0
	global_load_lds_dwordx4 v[144:145], off
	v_lshl_add_u64 v[144:145], v[218:219], 0, s[6:7]
	s_mov_b32 m0, s48
	s_nop 0
	global_load_lds_dwordx4 v[144:145], off
	v_lshl_add_u64 v[144:145], v[220:221], 0, s[6:7]
	s_mov_b32 m0, s49
	s_nop 0
	global_load_lds_dwordx4 v[144:145], off
	s_waitcnt vmcnt(8)
	s_waitcnt lgkmcnt(0)
	s_barrier
	s_setprio 1
	s_waitcnt lgkmcnt(0)
	v_mfma_f32_16x16x32_bf16 v[60:63], v[152:155], v[184:187], v[60:63]
	v_mfma_f32_16x16x32_bf16 v[60:63], v[156:159], v[188:191], v[60:63]
	v_mfma_f32_16x16x32_bf16 v[56:59], v[160:163], v[184:187], v[56:59]
	v_mfma_f32_16x16x32_bf16 v[56:59], v[164:167], v[188:191], v[56:59]
	v_mfma_f32_16x16x32_bf16 v[44:47], v[152:155], v[192:195], v[44:47]
	v_mfma_f32_16x16x32_bf16 v[44:47], v[156:159], v[196:199], v[44:47]
	v_mfma_f32_16x16x32_bf16 v[40:43], v[160:163], v[192:195], v[40:43]
	v_mfma_f32_16x16x32_bf16 v[40:43], v[164:167], v[196:199], v[40:43]
	v_mfma_f32_16x16x32_bf16 v[28:31], v[152:155], v[200:203], v[28:31]
	v_mfma_f32_16x16x32_bf16 v[28:31], v[156:159], v[204:207], v[28:31]
	v_mfma_f32_16x16x32_bf16 v[24:27], v[160:163], v[200:203], v[24:27]
	v_mfma_f32_16x16x32_bf16 v[24:27], v[164:167], v[204:207], v[24:27]
	v_mfma_f32_16x16x32_bf16 v[12:15], v[152:155], v[208:211], v[12:15]
	v_mfma_f32_16x16x32_bf16 v[12:15], v[156:159], v[212:215], v[12:15]
	v_mfma_f32_16x16x32_bf16 v[8:11], v[160:163], v[208:211], v[8:11]
	v_mfma_f32_16x16x32_bf16 v[8:11], v[164:167], v[212:215], v[8:11]
	s_setprio 0
	s_setprio 1
	v_mfma_f32_16x16x32_bf16 v[52:55], v[168:171], v[184:187], v[52:55]
	v_mfma_f32_16x16x32_bf16 v[52:55], v[172:175], v[188:191], v[52:55]
	v_mfma_f32_16x16x32_bf16 v[48:51], v[176:179], v[184:187], v[48:51]
	v_mfma_f32_16x16x32_bf16 v[48:51], v[180:183], v[188:191], v[48:51]
	v_mfma_f32_16x16x32_bf16 v[36:39], v[168:171], v[192:195], v[36:39]
	v_mfma_f32_16x16x32_bf16 v[36:39], v[172:175], v[196:199], v[36:39]
	v_mfma_f32_16x16x32_bf16 v[32:35], v[176:179], v[192:195], v[32:35]
	v_mfma_f32_16x16x32_bf16 v[32:35], v[180:183], v[196:199], v[32:35]
	v_mfma_f32_16x16x32_bf16 v[20:23], v[168:171], v[200:203], v[20:23]
	v_mfma_f32_16x16x32_bf16 v[20:23], v[172:175], v[204:207], v[20:23]
	v_mfma_f32_16x16x32_bf16 v[16:19], v[176:179], v[200:203], v[16:19]
	v_mfma_f32_16x16x32_bf16 v[16:19], v[180:183], v[204:207], v[16:19]
	v_mfma_f32_16x16x32_bf16 v[4:7], v[168:171], v[208:211], v[4:7]
	v_mfma_f32_16x16x32_bf16 v[4:7], v[172:175], v[212:215], v[4:7]
	v_mfma_f32_16x16x32_bf16 v[0:3], v[176:179], v[208:211], v[0:3]
	v_mfma_f32_16x16x32_bf16 v[0:3], v[180:183], v[212:215], v[0:3]
	s_setprio 0
	s_barrier
	s_mov_b32 s99, 0
	s_add_i32 s68, s68, 2
	s_add_u32 s28, s28, 0x100
	s_addc_u32 s29, s29, 0
	s_add_u32 s66, s66, 0x100
	s_addc_u32 s67, s67, 0
	s_cmp_gt_u32 s68, 61
	s_cbranch_scc0 .LBB0_2136
	v_and_b32_e32 v216, 0xfffffff7, v146
	v_lshl_add_u32 v216, s26, 8, v216
	v_bfe_u32 v220, v146, 3, 1
	v_lshl_add_u32 v220, v220, 2, v148
	v_lshl_or_b32 v220, s63, 8, v220
	v_ashrrev_i32_e32 v217, 31, v216
	v_ashrrev_i32_e32 v221, 31, v220
	v_lshlrev_b64 v[216:217], 12, v[216:217]
	v_lshlrev_b64 v[220:221], 2, v[220:221]
	v_lshl_add_u64 v[216:217], s[84:85], 0, v[216:217]
	v_lshl_add_u64 v[216:217], v[216:217], 0, v[220:221]
	s_mov_b64 s[98:99], 0x8000
	v_lshl_add_u64 v[218:219], v[216:217], 0, s[98:99]
	v_mov_b64_e32 v[220:221], v[216:217]
	v_mov_b64_e32 v[222:223], v[218:219]
	s_mov_b64 s[98:99], 0x10000
	s_mov_b64 s[100:101], 0x50000
	global_load_dwordx4 v[152:155], v[216:217], off
	global_load_dwordx4 v[156:159], v[218:219], off
	global_load_dwordx4 v[160:163], v[216:217], off offset:512
	global_load_dwordx4 v[164:167], v[218:219], off offset:512
	v_lshl_add_u64 v[216:217], v[216:217], 0, s[98:99]
	v_lshl_add_u64 v[218:219], v[218:219], 0, s[98:99]
	global_load_dwordx4 v[168:171], v[216:217], off
	global_load_dwordx4 v[172:175], v[218:219], off
	global_load_dwordx4 v[176:179], v[216:217], off offset:512
	global_load_dwordx4 v[180:183], v[218:219], off offset:512
	v_lshl_add_u64 v[216:217], v[216:217], 0, s[98:99]
	v_lshl_add_u64 v[218:219], v[218:219], 0, s[98:99]
	global_load_dwordx4 v[184:187], v[216:217], off
	global_load_dwordx4 v[188:191], v[218:219], off
	global_load_dwordx4 v[192:195], v[216:217], off offset:512
	global_load_dwordx4 v[196:199], v[218:219], off offset:512
	v_lshl_add_u64 v[216:217], v[216:217], 0, s[98:99]
	v_lshl_add_u64 v[218:219], v[218:219], 0, s[98:99]
	global_load_dwordx4 v[200:203], v[216:217], off
	global_load_dwordx4 v[204:207], v[218:219], off
	global_load_dwordx4 v[208:211], v[216:217], off offset:512
	global_load_dwordx4 v[212:215], v[218:219], off offset:512
	v_lshl_add_u64 v[216:217], v[216:217], 0, s[100:101]
	v_lshl_add_u64 v[218:219], v[218:219], 0, s[100:101]
	global_load_dwordx4 v[228:231], v[216:217], off
	global_load_dwordx4 v[232:235], v[218:219], off
	global_load_dwordx4 v[236:239], v[216:217], off offset:512
	global_load_dwordx4 v[240:243], v[218:219], off offset:512
	v_lshl_add_u64 v[216:217], v[216:217], 0, s[98:99]
	v_lshl_add_u64 v[218:219], v[218:219], 0, s[98:99]
	s_and_b64 vcc, exec, s[8:9]
	s_cbranch_vccz .LBB0_2139
	s_barrier
